# attention loop: p0 sub+exp2 block moved from the MFMA-free pre-barrier tail into P.V MFMA gaps (exp results in new v240-255), H1 p1 subs moved behind barrier into LDS-read shadow
# speedup vs baseline: 1.0068x; 1.0068x over previous
; #define LAS __attribute__((address_space(3)))
; DI int v_st(int k, int c) { const int kk = (k & ~0xC) | ((k & 4) << 1) | ((k & 8) >> 1); return ((kk >> 3) * 4 + (c >> 5)) * 512 + ((kk & 7) * 32 + (c & 31)) * 2; }
; DI int v_rd_base(int lane) { return ((lane & 3) << 3) | (((lane >> 2) & 3) << 6) | (((lane >> 4) & 1) << 5) | (((lane >> 5) & 1) << 8); }
; #define SLOAD(k0) do { vs0 = *(const bf16x8*)(&Vh[(long)((k0) + sr) * LDK + sc]); vs1 = *(const bf16x8*)(&Vh[(long)((k0) + 32 + sr) * LDK + sc]); \
;     ks0 = *(const bf16x8*)(&Kh[(long)((k0) + sr) * LDK + sc]); ks1 = *(const bf16x8*)(&Kh[(long)((k0) + 32 + sr) * LDK + sc]); \
;     ps0 = *(const bf16x8*)(&Ph[(long)((k0) + pr) * LDP + pc]); } while (0)
; #define SWAIT() asm volatile("s_waitcnt vmcnt(0)" ::: "memory")
; DI void attn_unit(const bf16_t* __restrict__ Qb, const bf16_t* __restrict__ Kh, const bf16_t* __restrict__ Vh, const bf16_t* __restrict__ Ph,
;                   bf16_t* __restrict__ Ob, int seq, float* __restrict__ lse_out, char* lds) {
;   constexpr int LDQ = 1536, LDK = 2048, LDP = 64, LDO = 1024;
;   int tid = threadIdx.x; asm volatile("" : "+v"(tid));
;   const int wid = tid >> 6, lane = tid & 63, r32 = lane & 31, hi = lane >> 5;
;   constexpr int A_STG = 40960, A_KO = 16384, A_PO = 32768;
;   float* wsf = (float*)(lds + 155648) + wid * 64; float* li_l = wsf; float* al_l = wsf + 32;
;   float m_reg = -1e30f, l_reg = 0; f32x16 o[4] = {}; bf16x8 qr[8];
;   char* QP = lds + 122880 + wid * 4096 + lane * 16;
;   const bf16_t* Qw = Qb + (long)(wid * 32 + r32) * LDQ + hi * 8;
; #pragma unroll
;   for (int d0 = 0; d0 < 8; ++d0) qr[d0] = *reinterpret_cast<const bf16x8*>(Qw + d0 * 16);
; #pragma unroll
;   for (int d0 = 0; d0 < 4; ++d0) *reinterpret_cast<bf16x8*>(QP + d0 * 1024) = *reinterpret_cast<const bf16x8*>(Qw + 128 + d0 * 16);
;   const int sr = tid >> 4, sc = (tid & 15) * 8, vst0 = v_st(sr, sc), vst1 = v_st(32 + sr, sc);
;   const int pr = tid >> 3, pc = (tid & 7) * 8;
;   const int vb0 = (int)(unsigned)(size_t)(LAS char*)lds + v_rd_base(lane);
;   bf16x8 vs0, vs1, ks0, ks1, ps0;
;     ...
;   f32x16 pA0, pA1, pB0, pB1; float mnA, mnB, alA, alB; bf16x8 pa0, pa1, pa2, pa3; const int NT = seq / 64;
;   SLOAD(0); SWAIT(); SWRITE(0); __syncthreads();
.LBB0_664:
	s_lshl_b32 s3, s6, 8
	s_ashr_i32 s6, s3, 31
	s_add_u32 s34, s4, s3
	s_addc_u32 s35, s5, s6
	s_add_i32 s20, s4, s2
	s_mul_i32 s2, s35, 0xc00
	s_mul_hi_u32 s3, s34, 0xc00
	s_add_i32 s3, s3, s2
	s_mul_i32 s2, s34, 0xc00
	v_mov_b32_e32 v54, v1
	s_add_u32 s4, s95, s2
	s_addc_u32 s5, s96, s3
	v_ashrrev_i32_e32 v55, 6, v54
	v_and_b32_e32 v159, 31, v54
	v_lshlrev_b32_e32 v136, 5, v55
	v_bfe_u32 v160, v54, 5, 1
	v_or_b32_e32 v138, v136, v159
	v_mov_b64_e32 v[2:3], s[4:5]
	s_movk_i32 s4, 0xc00
	v_mad_i64_i32 v[2:3], s[4:5], v138, s4, v[2:3]
	v_lshlrev_b32_e32 v134, 4, v160
	v_lshl_add_u64 v[42:43], v[2:3], 0, v[134:135]
	v_ashrrev_i32_e32 v50, 4, v54
	global_load_dwordx4 v[6:9], v[42:43], off offset:256
	global_load_dwordx4 v[10:13], v[42:43], off offset:288
	global_load_dwordx4 v[14:17], v[42:43], off offset:320
	global_load_dwordx4 v[18:21], v[42:43], off offset:352
	v_lshlrev_b32_e32 v56, 3, v54
	v_add_u32_e32 v44, 32, v50
	s_lshl_b64 s[2:3], s[20:21], 12
	v_and_b32_e32 v2, 0x78, v56
	v_ashrrev_i32_e32 v51, 31, v50
	v_ashrrev_i32_e32 v45, 31, v44
	s_add_u32 s2, s97, s2
	v_lshlrev_b32_e32 v57, 1, v2
	v_lshlrev_b64 v[2:3], 12, v[50:51]
	v_lshlrev_b64 v[4:5], 12, v[44:45]
	s_addc_u32 s3, s33, s3
	v_or_b32_e32 v2, v2, v57
	v_or_b32_e32 v4, v4, v57
	s_lshl_b64 s[36:37], s[20:21], 7
	v_ashrrev_i32_e32 v46, 3, v54
	v_lshl_add_u64 v[2:3], s[2:3], 0, v[2:3]
	v_lshl_add_u64 v[4:5], s[2:3], 0, v[4:5]
	s_add_u32 s2, s38, s36
	v_ashrrev_i32_e32 v47, 31, v46
	s_addc_u32 s3, s39, s37
	v_lshlrev_b64 v[52:53], 7, v[46:47]
	v_lshlrev_b32_e32 v45, 4, v54
	global_load_dwordx4 v[22:25], v[2:3], off offset:256
	global_load_dwordx4 v[26:29], v[4:5], off offset:256
	global_load_dwordx4 v[30:33], v[2:3], off
	global_load_dwordx4 v[34:37], v[4:5], off
	v_lshl_add_u64 v[4:5], s[2:3], 0, v[52:53]
	v_and_b32_e32 v48, 0x70, v45
	v_mov_b32_e32 v49, v135
	v_lshl_add_u64 v[4:5], v[4:5], 0, v[48:49]
	global_load_dwordx4 v[38:41], v[4:5], off
	global_load_dwordx4 v[114:117], v[42:43], off
	global_load_dwordx4 v[118:121], v[42:43], off offset:32
	global_load_dwordx4 v[126:129], v[42:43], off offset:64
	global_load_dwordx4 v[122:125], v[42:43], off offset:96
	global_load_dwordx4 v[110:113], v[42:43], off offset:128
	global_load_dwordx4 v[106:109], v[42:43], off offset:160
	global_load_dwordx4 v[102:105], v[42:43], off offset:192
	global_load_dwordx4 v[98:101], v[42:43], off offset:224
	v_and_b32_e32 v84, 63, v54
	v_lshlrev_b32_e32 v80, 4, v84
	v_lshl_add_u32 v47, v55, 12, s52
	v_and_b32_e32 v49, 0xfffff0, v50
	v_lshlrev_b32_e32 v55, 1, v50
	v_lshrrev_b32_e32 v58, 1, v50
	v_and_b32_e32 v60, 3, v50
	v_add_u32_e32 v163, v47, v80
	v_and_or_b32 v47, v55, 8, v49
	v_and_or_b32 v49, v58, 4, v60
	v_and_b32_e32 v55, 0xfffff0, v44
	v_lshlrev_b32_e32 v58, 1, v44
	v_and_or_b32 v55, v58, 8, v55
	v_bfe_u32 v59, v56, 5, 2
	v_lshrrev_b32_e32 v55, 1, v55
	v_lshlrev_b32_e32 v49, 6, v49
	v_and_b32_e32 v60, 48, v57
	v_lshrrev_b32_e32 v47, 1, v47
	v_or_b32_e32 v47, v47, v59
	v_lshlrev_b32_e32 v47, 9, v47
	v_or3_b32 v164, v47, v49, v60
	v_or_b32_e32 v81, 64, v134
	v_or_b32_e32 v82, 0x60, v134
	v_lshlrev_b32_e32 v83, 7, v159
	v_and_b32_e32 v89, 0x70, v56
	v_bitop3_b32 v179, v134, v83, v89 bitop3:0xde
	s_mov_b64 s[2:3], 0x40000
	v_bitop3_b32 v181, v81, v83, v89 bitop3:0xde
	v_bitop3_b32 v182, v82, v83, v89 bitop3:0xde
	s_mov_b32 s4, 0
	v_lshl_add_u64 v[140:141], v[52:53], 0, s[36:37]
	s_mov_b32 s5, s4
	s_mov_b32 s6, s4
	s_waitcnt vmcnt(16)
	ds_write_b128 v163, v[6:9]
	s_waitcnt vmcnt(15)
	ds_write_b128 v163, v[10:13] offset:1024
	s_waitcnt vmcnt(14)
	ds_write_b128 v163, v[14:17] offset:2048
	s_waitcnt vmcnt(13)
	ds_write_b128 v163, v[18:21] offset:3072
	v_or_b32_e32 v6, v55, v59
	v_lshlrev_b32_e32 v6, 9, v6
	v_or3_b32 v165, v6, v49, v60
	v_lshlrev_b32_e32 v6, 8, v50
	v_and_b32_e32 v7, 0xf0, v54
	v_bitop3_b32 v167, v57, v6, v7 bitop3:0xde
	v_lshlrev_b32_e32 v6, 8, v44
	v_bitop3_b32 v168, v57, v6, v7 bitop3:0xde
	v_lshlrev_b32_e32 v6, 7, v46
	v_and_b32_e32 v7, 0x70, v54
	v_lshlrev_b32_e32 v14, 8, v159
	v_and_b32_e32 v15, 0xf0, v45
	v_bitop3_b32 v169, v48, v6, v7 bitop3:0xde
	v_bitop3_b32 v170, v134, v14, v15 bitop3:0xde
	v_add_u32_e32 v55, 0, v164
	v_add_u32_e32 v85, 0, v165
	v_add_u32_e32 v86, 0, v167
	v_add_u32_e32 v87, 0, v168
	v_add_u32_e32 v88, 0, v169
	v_add_u32_e32 v10, 0, v170
	s_waitcnt vmcnt(0)
	v_or_b32_e32 v60, 32, v134
	s_waitcnt vmcnt(12)
	ds_write_b128 v55, v[22:25]
	s_waitcnt vmcnt(11)
	ds_write_b128 v85, v[26:29]
	s_waitcnt vmcnt(10)
	ds_write_b128 v86, v[30:33] offset:16384
	s_waitcnt vmcnt(9)
	ds_write_b128 v87, v[34:37] offset:16384
	v_bitop3_b32 v172, v60, v14, v15 bitop3:0xde
	v_bitop3_b32 v173, v81, v14, v15 bitop3:0xde
	s_waitcnt vmcnt(8)
	ds_write_b128 v88, v[38:41] offset:32768
	s_waitcnt lgkmcnt(0)
	s_barrier
; #define MFMA32(a, b, c) __builtin_amdgcn_mfma_f32_32x32x16_bf16((a), (b), (c), 0, 0, 0)
; #define SLOAD(k0) do { vs0 = *(const bf16x8*)(&Vh[(long)((k0) + sr) * LDK + sc]); vs1 = *(const bf16x8*)(&Vh[(long)((k0) + 32 + sr) * LDK + sc]); \
;     ks0 = *(const bf16x8*)(&Kh[(long)((k0) + sr) * LDK + sc]); ks1 = *(const bf16x8*)(&Kh[(long)((k0) + 32 + sr) * LDK + sc]); \
;     ps0 = *(const bf16x8*)(&Ph[(long)((k0) + pr) * LDP + pc]); } while (0)
; #define SWRITE(st) do { char* b_ = lds + (st); *(bf16x8*)(b_ + vst0) = vs0; *(bf16x8*)(b_ + vst1) = vs1; const int kc = sc * 2; \
;     *(bf16x8*)(b_ + A_KO + KSWZ(sr, kc)) = ks0; *(bf16x8*)(b_ + A_KO + KSWZ(32 + sr, kc)) = ks1; \
;     *(bf16x8*)(b_ + A_PO + PSWZ(pr, pc * 2)) = ps0; } while (0)
; #define SWAIT() asm volatile("s_waitcnt vmcnt(0)" ::: "memory")
; DI void a_qkt(f32x16& p0, f32x16& p1, const char* Ks, const char* Ps, const bf16x8* qr, const char* QP, int r32, int hi) {
;   p0 = f32x16{}; p1 = f32x16{};
; #pragma unroll
;   for (int d0 = 0; d0 < 8; ++d0) { const int cb = (d0 * 16 + hi * 8) * 2;
;     bf16x8 b0 = *reinterpret_cast<const bf16x8*>(Ks + KSWZ(r32, cb));
;     bf16x8 b1 = *reinterpret_cast<const bf16x8*>(Ks + KSWZ(32 + r32, cb));
;     p0 = MFMA32(b0, qr[d0], p0);
;     p1 = MFMA32(b1, qr[d0], p1); }
; #pragma unroll
;   for (int d0 = 0; d0 < 4; ++d0) { const int cb = (d0 * 16 + hi * 8) * 2;
;     bf16x8 b0 = *reinterpret_cast<const bf16x8*>(Ps + PSWZ(r32, cb));
;     bf16x8 b1 = *reinterpret_cast<const bf16x8*>(Ps + PSWZ(32 + r32, cb));
;     const bf16x8 qp = *reinterpret_cast<const bf16x8*>(QP + d0 * 1024);
;     p0 = MFMA32(b0, qp, p0);
;     p1 = MFMA32(b1, qp, p1); }
; }
; DI void attn_unit(const bf16_t* __restrict__ Qb, const bf16_t* __restrict__ Kh, const bf16_t* __restrict__ Vh, const bf16_t* __restrict__ Ph,
;                   bf16_t* __restrict__ Ob, int seq, float* __restrict__ lse_out, char* lds) {
;     ...
;   a_qkt(pA0, pA1, lds + A_KO, lds + A_PO, qr, QP, r32, hi); a_partialSM(pA0, pA1, m_reg, mnA, alA);
;   SLOAD(64);
;   SWAIT(); SWRITE(A_STG); __syncthreads();
	ds_read_b128 v[6:9], v10 offset:16384
	ds_read_b128 v[10:13], v10 offset:24576
	s_waitcnt vmcnt(7) lgkmcnt(1)
	v_mfma_f32_32x32x16_bf16 v[34:49], v[6:9], v[114:117], 0
	v_bitop3_b32 v174, v82, v14, v15 bitop3:0xde
	v_bitop3_b32 v180, v60, v83, v89 bitop3:0xde
	s_mov_b32 s7, s4
	s_mov_b32 s8, s4
	s_mov_b32 s9, s4
	s_mov_b32 s10, s4
	s_mov_b32 s11, s4
	s_waitcnt lgkmcnt(0)
	v_mfma_f32_32x32x16_bf16 v[18:33], v[10:13], v[114:117], 0
	v_add_u32_e32 v10, 0, v172
	ds_read_b128 v[6:9], v10 offset:16384
	ds_read_b128 v[10:13], v10 offset:24576
	s_mov_b32 s12, s4
	s_mov_b32 s13, s4
	s_mov_b32 s14, s4
	s_mov_b32 s15, s4
	s_mov_b32 s16, s4
	s_waitcnt vmcnt(6) lgkmcnt(1)
	v_mfma_f32_32x32x16_bf16 v[34:49], v[6:9], v[118:121], v[34:49]
	s_mov_b32 s17, s4
	s_mov_b32 s18, s4
	s_mov_b32 s19, s4
	s_mov_b32 s66, 2
	v_ashrrev_i32_e32 v139, 31, v138
	v_mov_b32_e32 v162, 0
	s_waitcnt lgkmcnt(0)
	v_mfma_f32_32x32x16_bf16 v[18:33], v[10:13], v[118:121], v[18:33]
	v_add_u32_e32 v10, 0, v173
	ds_read_b128 v[6:9], v10 offset:16384
	ds_read_b128 v[10:13], v10 offset:24576
	s_waitcnt vmcnt(5) lgkmcnt(1)
	v_mfma_f32_32x32x16_bf16 v[34:49], v[6:9], v[126:129], v[34:49]
	s_waitcnt lgkmcnt(0)
	v_mfma_f32_32x32x16_bf16 v[18:33], v[10:13], v[126:129], v[18:33]
	v_add_u32_e32 v10, 0, v174
	ds_read_b128 v[6:9], v10 offset:16384
	ds_read_b128 v[10:13], v10 offset:24576
	s_waitcnt vmcnt(4) lgkmcnt(1)
	v_mfma_f32_32x32x16_bf16 v[34:49], v[6:9], v[122:125], v[34:49]
	v_or_b32_e32 v6, 0x80, v134
	v_bitop3_b32 v175, v6, v14, v15 bitop3:0xde
	s_waitcnt lgkmcnt(0)
	v_mfma_f32_32x32x16_bf16 v[18:33], v[10:13], v[122:125], v[18:33]
	v_add_u32_e32 v10, 0, v175
	ds_read_b128 v[6:9], v10 offset:16384
	ds_read_b128 v[10:13], v10 offset:24576
	s_waitcnt vmcnt(3) lgkmcnt(1)
	v_mfma_f32_32x32x16_bf16 v[34:49], v[6:9], v[110:113], v[34:49]
	v_or_b32_e32 v6, 0xa0, v134
	v_bitop3_b32 v176, v6, v14, v15 bitop3:0xde
	s_waitcnt lgkmcnt(0)
	v_mfma_f32_32x32x16_bf16 v[18:33], v[10:13], v[110:113], v[18:33]
	v_add_u32_e32 v10, 0, v176
	ds_read_b128 v[6:9], v10 offset:16384
	ds_read_b128 v[10:13], v10 offset:24576
	s_waitcnt vmcnt(2) lgkmcnt(1)
	v_mfma_f32_32x32x16_bf16 v[34:49], v[6:9], v[106:109], v[34:49]
	v_or_b32_e32 v6, 0xc0, v134
	v_bitop3_b32 v177, v6, v14, v15 bitop3:0xde
	s_waitcnt lgkmcnt(0)
	v_mfma_f32_32x32x16_bf16 v[18:33], v[10:13], v[106:109], v[18:33]
	v_add_u32_e32 v10, 0, v177
	ds_read_b128 v[6:9], v10 offset:16384
	ds_read_b128 v[10:13], v10 offset:24576
	s_waitcnt vmcnt(1) lgkmcnt(1)
	v_mfma_f32_32x32x16_bf16 v[34:49], v[6:9], v[102:105], v[34:49]
	v_or_b32_e32 v6, 0xe0, v134
	v_bitop3_b32 v178, v6, v14, v15 bitop3:0xde
	v_add_u32_e32 v14, 0, v179
	s_waitcnt lgkmcnt(0)
	v_mfma_f32_32x32x16_bf16 v[18:33], v[10:13], v[102:105], v[18:33]
	v_add_u32_e32 v10, 0, v178
	ds_read_b128 v[6:9], v10 offset:16384
	ds_read_b128 v[10:13], v10 offset:24576
	s_waitcnt vmcnt(0) lgkmcnt(1)
	v_mfma_f32_32x32x16_bf16 v[34:49], v[6:9], v[98:101], v[34:49]
	s_waitcnt lgkmcnt(0)
	v_mfma_f32_32x32x16_bf16 v[18:33], v[10:13], v[98:101], v[18:33]
	ds_read_b128 v[6:9], v14 offset:32768
	ds_read_b128 v[10:13], v163
	ds_read_b128 v[14:17], v14 offset:36864
	ds_read_b128 v[56:59], v163 offset:1024
	s_waitcnt lgkmcnt(2)
	v_mfma_f32_32x32x16_bf16 v[34:49], v[6:9], v[10:13], v[34:49]
	s_waitcnt lgkmcnt(1)
	v_mfma_f32_32x32x16_bf16 v[18:33], v[14:17], v[10:13], v[18:33]
	v_lshl_add_u64 v[10:11], v[2:3], 0, s[2:3]
	s_mov_b64 s[2:3], 0x60000
	v_add_u32_e32 v14, 0, v180
	v_lshl_add_u64 v[12:13], v[2:3], 0, s[2:3]
	s_mov_b32 s2, 0x40000
	ds_read_b128 v[6:9], v14 offset:32768
	global_load_dwordx4 v[60:63], v[10:11], off offset:256
	global_load_dwordx4 v[64:67], v[12:13], off offset:256
	v_add_co_u32_e32 v10, vcc, s2, v2
	s_mov_b32 s2, 0x60000
	s_nop 0
	v_addc_co_u32_e32 v11, vcc, 0, v3, vcc
	v_add_co_u32_e32 v2, vcc, s2, v2
	s_waitcnt lgkmcnt(0)
	v_mfma_f32_32x32x16_bf16 v[34:49], v[6:9], v[56:59], v[34:49]
	v_addc_co_u32_e32 v3, vcc, 0, v3, vcc
	global_load_dwordx4 v[68:71], v[10:11], off
	global_load_dwordx4 v[72:75], v[2:3], off
	v_add_co_u32_e32 v2, vcc, s55, v4
	v_lshlrev_b32_e32 v10, 3, v84
	s_nop 0
	v_addc_co_u32_e32 v3, vcc, 0, v5, vcc
	global_load_dwordx4 v[76:79], v[2:3], off
	v_and_b32_e32 v2, 0x3fffffc0, v54
	v_lshl_add_u32 v137, v2, 2, s51
	ds_read_b128 v[2:5], v14 offset:36864
	v_and_b32_e32 v6, 0xc0, v80
	v_add_u32_e32 v13, 0, v181
	v_and_or_b32 v11, v10, 24, v6
	ds_read_b128 v[6:9], v13 offset:32768
	s_waitcnt lgkmcnt(1)
	v_mfma_f32_32x32x16_bf16 v[18:33], v[2:5], v[56:59], v[18:33]
	ds_read_b128 v[2:5], v163 offset:2048
	v_lshlrev_b32_e32 v12, 1, v54
	v_and_b32_e32 v12, 32, v12
	v_and_b32_e32 v10, 0x100, v10
	v_or3_b32 v10, v11, v12, v10
	v_add_u32_e32 v14, 0, v182
	v_add_u32_e32 v171, 0, v10
	ds_read_b128 v[10:13], v13 offset:36864
	ds_read_b128 v[56:59], v163 offset:3072
	s_waitcnt lgkmcnt(2)
	v_mfma_f32_32x32x16_bf16 v[34:49], v[6:9], v[2:5], v[34:49]
	ds_read_b128 v[6:9], v14 offset:32768
	ds_read_b128 v[80:83], v14 offset:36864
	s_waitcnt vmcnt(0)
	s_waitcnt vmcnt(4)
	ds_write_b128 v55, v[60:63] offset:40960
	s_waitcnt vmcnt(3)
	ds_write_b128 v85, v[64:67] offset:40960
	s_waitcnt vmcnt(2)
	ds_write_b128 v86, v[68:71] offset:57344
	s_waitcnt vmcnt(1)
	ds_write_b128 v87, v[72:75] offset:57344
	s_waitcnt lgkmcnt(7)
	v_mfma_f32_32x32x16_bf16 v[18:33], v[10:13], v[2:5], v[18:33]
	v_add_u32_e32 v55, 0x12000, v88
	v_cmp_gt_u32_e64 s[2:3], 32, v84
	v_lshl_add_u32 v161, v159, 2, v137
	s_waitcnt vmcnt(0)
	ds_write_b128 v55, v[76:79]
	s_waitcnt lgkmcnt(0)
	s_barrier
; DI void a_partialSM(f32x16& p0, f32x16& p1, float& m_reg, float& mn, float& alpha) {
;   float pmax = p0[0];
; #pragma unroll
;   for (int r = 1; r < 16; ++r) pmax = fmaxf(pmax, p0[r]);
; #pragma unroll
;   for (int r = 0; r < 16; ++r) pmax = fmaxf(pmax, p1[r]);
;   { auto rr = __builtin_amdgcn_permlane32_swap(__float_as_uint(pmax), __float_as_uint(pmax), false, false);
;     pmax = fmaxf(__uint_as_float(rr[0]), __uint_as_float(rr[1])); }
;   if (__builtin_expect(__all(pmax - m_reg <= ATH), 1)) { mn = m_reg; alpha = 1.f; }
;   else { mn = fmaxf(m_reg, pmax); alpha = __builtin_amdgcn_exp2f(m_reg - mn); m_reg = mn; }
; #pragma unroll
;   for (int r = 0; r < 16; ++r) p0[r] = p0[r] - mn;
; #pragma unroll
;   for (int r = 0; r < 16; ++r) p1[r] = p1[r] - mn;
; #pragma unroll
;   for (int r = 0; r < 16; ++r) p0[r] = __builtin_amdgcn_exp2f(p0[r]);
; }
	v_mfma_f32_32x32x16_bf16 v[34:49], v[6:9], v[56:59], v[34:49]
	v_mov_b64_e32 v[2:3], s[4:5]
	v_mov_b64_e32 v[16:17], s[18:19]
	v_mov_b64_e32 v[4:5], s[6:7]
	v_mov_b64_e32 v[6:7], s[8:9]
	v_mov_b64_e32 v[8:9], s[10:11]
	v_mov_b64_e32 v[10:11], s[12:13]
	v_mov_b64_e32 v[12:13], s[14:15]
	v_mfma_f32_32x32x16_bf16 v[18:33], v[80:83], v[56:59], v[18:33]
	s_nop 3
	v_max_f32_e32 v56, v35, v35
	v_max_f32_e32 v57, v34, v34
	v_max_f32_e32 v56, v57, v56
	v_max3_f32 v56, v56, v36, v37
	v_max3_f32 v56, v56, v38, v39
	v_max3_f32 v56, v56, v40, v41
	v_max3_f32 v56, v56, v42, v43
	v_max3_f32 v56, v56, v44, v45
	v_max3_f32 v56, v56, v46, v47
	v_max3_f32 v56, v56, v48, v49
	v_max3_f32 v56, v56, v18, v19
	v_max3_f32 v56, v56, v20, v21
	v_max3_f32 v56, v56, v22, v23
	v_max3_f32 v56, v56, v24, v25
	v_max3_f32 v56, v56, v26, v27
	v_max3_f32 v56, v56, v28, v29
	v_max3_f32 v56, v56, v30, v31
	v_max3_f32 v56, v56, v32, v33
	v_mov_b32_e32 v57, v56
	s_nop 1
	v_permlane32_swap_b32_e32 v56, v57
	v_max_f32_e32 v57, v57, v57
	v_max_f32_e32 v56, v56, v56
	v_max_f32_e32 v56, v56, v57
	v_add_f32_e32 v57, 0x7149f2ca, v56
	v_cmp_ge_f32_e32 vcc, s54, v57
	s_cmp_eq_u64 vcc, exec
	v_max_f32_e32 v55, 0xf149f2ca, v56
	s_cselect_b64 vcc, -1, 0
	v_cndmask_b32_e32 v144, v55, v158, vcc
	v_sub_f32_e32 v34, v34, v144
	v_exp_f32_e32 v191, v34
	v_sub_f32_e32 v34, v35, v144
	v_exp_f32_e32 v192, v34
	v_sub_f32_e32 v34, v36, v144
	v_exp_f32_e32 v194, v34
	v_sub_f32_e32 v34, v37, v144
	v_exp_f32_e32 v196, v34
	v_sub_f32_e32 v34, v38, v144
	v_exp_f32_e32 v198, v34
	v_sub_f32_e32 v34, v39, v144
	v_exp_f32_e32 v200, v34
	v_sub_f32_e32 v34, v40, v144
	v_exp_f32_e32 v197, v34
	v_sub_f32_e32 v34, v41, v144
	v_exp_f32_e32 v199, v34
	v_sub_f32_e32 v34, v42, v144
	v_exp_f32_e32 v185, v34
	v_sub_f32_e32 v34, v43, v144
	v_exp_f32_e32 v186, v34
	v_sub_f32_e32 v34, v44, v144
	v_exp_f32_e32 v188, v34
	v_sub_f32_e32 v34, v45, v144
	v_exp_f32_e32 v190, v34
	v_sub_f32_e32 v34, v46, v144
	v_exp_f32_e32 v187, v34
	v_sub_f32_e32 v34, v47, v144
	v_sub_f32_e32 v35, 0xf149f2ca, v55
	v_exp_f32_e32 v189, v34
	v_sub_f32_e32 v34, v48, v144
	v_exp_f32_e32 v35, v35
	v_sub_f32_e32 v130, v18, v144
	v_and_b32_e32 v18, 7, v54
	v_exp_f32_e32 v193, v34
	v_sub_f32_e32 v34, v49, v144
	v_sub_f32_e32 v131, v19, v144
	v_lshl_or_b32 v140, v18, 4, v140
	v_lshl_add_u64 v[18:19], v[50:51], 0, s[20:21]
	v_exp_f32_e32 v195, v34
	v_sub_f32_e32 v146, v20, v144
	v_lshlrev_b64 v[18:19], 12, v[18:19]
	v_and_b32_e32 v20, 15, v54
	v_sub_f32_e32 v147, v21, v144
	v_or_b32_e32 v18, s91, v18
	v_lshlrev_b32_e32 v20, 4, v20
	v_mov_b32_e32 v21, v135
	v_mov_b64_e32 v[14:15], s[16:17]
	v_cndmask_b32_e64 v183, v35, 1.0, vcc
	v_sub_f32_e32 v132, v22, v144
	v_sub_f32_e32 v133, v23, v144
	v_sub_f32_e32 v148, v24, v144
	v_sub_f32_e32 v149, v25, v144
	v_sub_f32_e32 v150, v26, v144
	v_sub_f32_e32 v151, v27, v144
	v_sub_f32_e32 v154, v28, v144
	v_sub_f32_e32 v155, v29, v144
	v_sub_f32_e32 v152, v30, v144
	v_sub_f32_e32 v153, v31, v144
	v_sub_f32_e32 v156, v32, v144
	v_sub_f32_e32 v157, v33, v144
	v_lshl_add_u64 v[142:143], v[18:19], 0, v[20:21]
	v_mov_b64_e32 v[64:65], v[16:17]
	v_mov_b64_e32 v[48:49], v[16:17]
	v_mov_b64_e32 v[32:33], v[16:17]
	s_mov_b32 s7, 0xa000
	s_mov_b32 s6, 0x14000
	v_mov_b64_e32 v[62:63], v[14:15]
	v_mov_b64_e32 v[60:61], v[12:13]
	v_mov_b64_e32 v[58:59], v[10:11]
	v_mov_b64_e32 v[56:57], v[8:9]
	v_mov_b64_e32 v[54:55], v[6:7]
	v_mov_b64_e32 v[52:53], v[4:5]
	v_mov_b64_e32 v[50:51], v[2:3]
	v_mov_b64_e32 v[46:47], v[14:15]
	v_mov_b64_e32 v[44:45], v[12:13]
	v_mov_b64_e32 v[42:43], v[10:11]
	v_mov_b64_e32 v[40:41], v[8:9]
	v_mov_b64_e32 v[38:39], v[6:7]
	v_mov_b64_e32 v[36:37], v[4:5]
	v_mov_b64_e32 v[34:35], v[2:3]
	v_mov_b64_e32 v[30:31], v[14:15]
	v_mov_b64_e32 v[28:29], v[12:13]
	v_mov_b64_e32 v[26:27], v[10:11]
	v_mov_b64_e32 v[24:25], v[8:9]
	v_mov_b64_e32 v[22:23], v[6:7]
	v_mov_b64_e32 v[20:21], v[4:5]
	v_mov_b64_e32 v[18:19], v[2:3]
	v_mov_b32_e32 v240, v191
	v_mov_b32_e32 v241, v192
	v_mov_b32_e32 v242, v194
	v_mov_b32_e32 v243, v196
	v_mov_b32_e32 v244, v198
	v_mov_b32_e32 v245, v200
	v_mov_b32_e32 v246, v197
	v_mov_b32_e32 v247, v199
	v_mov_b32_e32 v248, v185
	v_mov_b32_e32 v249, v186
	v_mov_b32_e32 v250, v188
	v_mov_b32_e32 v251, v190
	v_mov_b32_e32 v252, v187
	v_mov_b32_e32 v253, v189
	v_mov_b32_e32 v254, v193
	v_mov_b32_e32 v255, v195
; #define MFMA32(a, b, c) __builtin_amdgcn_mfma_f32_32x32x16_bf16((a), (b), (c), 0, 0, 0)
; DI void a_finishSM(f32x16& p0, f32x16& p1, float alpha, float& l_reg, bf16x8& pa0, bf16x8& pa1, bf16x8& pa2, bf16x8& pa3) {
; #pragma unroll
;   for (int r = 0; r < 16; ++r) p1[r] = __builtin_amdgcn_exp2f(p1[r]);
;   float ps = 0;
; #pragma unroll
;   for (int r = 0; r < 16; ++r) ps += p0[r];
; #pragma unroll
;   for (int r = 0; r < 16; ++r) ps += p1[r];
;   { auto rr = __builtin_amdgcn_permlane32_swap(__float_as_uint(ps), __float_as_uint(ps), false, false);
;     ps = __uint_as_float(rr[0]) + __uint_as_float(rr[1]); }
;   l_reg = l_reg * alpha + ps;
;     ...
;   PK4(p0, 0, pa0); PK4(p0, 8, pa1); PK4(p1, 0, pa2); PK4(p1, 8, pa3);
; DI void a_qkt(f32x16& p0, f32x16& p1, const char* Ks, const char* Ps, const bf16x8* qr, const char* QP, int r32, int hi) {
;   p0 = f32x16{}; p1 = f32x16{};
; #pragma unroll
;   for (int d0 = 0; d0 < 8; ++d0) { const int cb = (d0 * 16 + hi * 8) * 2;
;     bf16x8 b0 = *reinterpret_cast<const bf16x8*>(Ks + KSWZ(r32, cb));
;     bf16x8 b1 = *reinterpret_cast<const bf16x8*>(Ks + KSWZ(32 + r32, cb));
;     p0 = MFMA32(b0, qr[d0], p0);
;     p1 = MFMA32(b1, qr[d0], p1); }
; #pragma unroll
;   for (int d0 = 0; d0 < 4; ++d0) { const int cb = (d0 * 16 + hi * 8) * 2;
;     bf16x8 b0 = *reinterpret_cast<const bf16x8*>(Ps + PSWZ(r32, cb));
;     bf16x8 b1 = *reinterpret_cast<const bf16x8*>(Ps + PSWZ(32 + r32, cb));
;     const bf16x8 qp = *reinterpret_cast<const bf16x8*>(QP + d0 * 1024);
;     p0 = MFMA32(b0, qp, p0);
;     p1 = MFMA32(b1, qp, p1); }
; }
.LBB0_665:
	s_mov_b32 s8, s4
	s_add_i32 s4, s7, 0
	v_add_u32_e32 v70, s4, v170
	ds_read_b128 v[66:69], v70 offset:16384
	ds_read_b128 v[82:85], v70 offset:24576
	v_add_u32_e32 v166, s4, v172
	ds_read_b128 v[202:205], v166 offset:16384
	ds_read_b128 v[206:209], v166 offset:24576
	v_add_u32_e32 v166, s4, v173
	s_waitcnt lgkmcnt(3)
	v_mfma_f32_32x32x16_bf16 v[66:81], v[66:69], v[114:117], 0
	v_exp_f32_e32 v184, v131
	v_exp_f32_e32 v146, v146
	v_exp_f32_e32 v147, v147
	v_exp_f32_e32 v201, v132
	v_exp_f32_e32 v148, v148
	v_exp_f32_e32 v149, v149
	v_exp_f32_e32 v152, v152
	s_waitcnt lgkmcnt(2)
	v_mfma_f32_32x32x16_bf16 v[82:97], v[82:85], v[114:117], 0
	v_exp_f32_e32 v153, v153
	v_cvt_pk_bf16_f32 v131, v242, v243
	v_cvt_pk_bf16_f32 v132, v244, v245
	s_waitcnt lgkmcnt(1)
	v_mfma_f32_32x32x16_bf16 v[66:81], v[202:205], v[118:121], v[66:81]
	s_waitcnt lgkmcnt(0)
	v_mfma_f32_32x32x16_bf16 v[82:97], v[206:209], v[118:121], v[82:97]
	ds_read_b128 v[202:205], v166 offset:16384
	ds_read_b128 v[206:209], v166 offset:24576
	v_add_u32_e32 v166, s4, v174
	s_waitcnt lgkmcnt(1)
	v_mfma_f32_32x32x16_bf16 v[66:81], v[202:205], v[126:129], v[66:81]
	s_waitcnt lgkmcnt(0)
	v_mfma_f32_32x32x16_bf16 v[82:97], v[206:209], v[126:129], v[82:97]
	ds_read_b128 v[202:205], v166 offset:16384
	ds_read_b128 v[206:209], v166 offset:24576
	v_add_u32_e32 v166, s4, v175
	s_waitcnt lgkmcnt(1)
	v_mfma_f32_32x32x16_bf16 v[66:81], v[202:205], v[122:125], v[66:81]
	s_waitcnt lgkmcnt(0)
	v_mfma_f32_32x32x16_bf16 v[82:97], v[206:209], v[122:125], v[82:97]
	ds_read_b128 v[202:205], v166 offset:16384
	ds_read_b128 v[206:209], v166 offset:24576
	v_add_u32_e32 v166, s4, v176
	s_waitcnt lgkmcnt(1)
	v_mfma_f32_32x32x16_bf16 v[66:81], v[202:205], v[110:113], v[66:81]
	s_waitcnt lgkmcnt(0)
	v_mfma_f32_32x32x16_bf16 v[82:97], v[206:209], v[110:113], v[82:97]
	ds_read_b128 v[202:205], v166 offset:16384
	ds_read_b128 v[206:209], v166 offset:24576
	v_add_u32_e32 v166, s4, v177
	s_waitcnt lgkmcnt(1)
	v_mfma_f32_32x32x16_bf16 v[66:81], v[202:205], v[106:109], v[66:81]
	s_waitcnt lgkmcnt(0)
	v_mfma_f32_32x32x16_bf16 v[82:97], v[206:209], v[106:109], v[82:97]
	ds_read_b128 v[202:205], v166 offset:16384
	ds_read_b128 v[206:209], v166 offset:24576
	v_add_u32_e32 v166, s4, v178
	s_waitcnt lgkmcnt(1)
	v_mfma_f32_32x32x16_bf16 v[66:81], v[202:205], v[102:105], v[66:81]
	s_waitcnt lgkmcnt(0)
	v_mfma_f32_32x32x16_bf16 v[82:97], v[206:209], v[102:105], v[82:97]
	ds_read_b128 v[202:205], v166 offset:16384
	ds_read_b128 v[206:209], v166 offset:24576
	v_add_u32_e32 v166, s4, v179
	s_waitcnt lgkmcnt(1)
	v_mfma_f32_32x32x16_bf16 v[66:81], v[202:205], v[98:101], v[66:81]
	s_waitcnt lgkmcnt(0)
	v_mfma_f32_32x32x16_bf16 v[82:97], v[206:209], v[98:101], v[82:97]
	ds_read_b128 v[202:205], v166 offset:32768
	ds_read_b128 v[206:209], v166 offset:36864
	ds_read_b128 v[210:213], v163
	v_add_u32_e32 v166, s4, v180
	s_waitcnt lgkmcnt(0)
	v_mfma_f32_32x32x16_bf16 v[66:81], v[202:205], v[210:213], v[66:81]
	v_mfma_f32_32x32x16_bf16 v[82:97], v[206:209], v[210:213], v[82:97]
	ds_read_b128 v[202:205], v166 offset:32768
	ds_read_b128 v[206:209], v166 offset:36864
	ds_read_b128 v[210:213], v163 offset:1024
	v_add_u32_e32 v166, s4, v181
	s_waitcnt lgkmcnt(0)
	v_mfma_f32_32x32x16_bf16 v[66:81], v[202:205], v[210:213], v[66:81]
	v_mfma_f32_32x32x16_bf16 v[82:97], v[206:209], v[210:213], v[82:97]
	ds_read_b128 v[202:205], v166 offset:32768
	ds_read_b128 v[206:209], v166 offset:36864
	ds_read_b128 v[210:213], v163 offset:2048
	v_add_u32_e32 v166, s4, v182
	s_waitcnt lgkmcnt(0)
	v_mfma_f32_32x32x16_bf16 v[66:81], v[202:205], v[210:213], v[66:81]
	v_mfma_f32_32x32x16_bf16 v[82:97], v[206:209], v[210:213], v[82:97]
	ds_read_b128 v[202:205], v166 offset:32768
	ds_read_b128 v[206:209], v166 offset:36864
	ds_read_b128 v[210:213], v163 offset:3072
	v_exp_f32_e32 v166, v130
	v_add_f32_e32 v130, 0, v240
	v_add_f32_e32 v130, v241, v130
	v_add_f32_e32 v130, v242, v130
	v_add_f32_e32 v130, v243, v130
	v_add_f32_e32 v130, v244, v130
	v_add_f32_e32 v130, v245, v130
	v_add_f32_e32 v130, v246, v130
	v_add_f32_e32 v130, v247, v130
	v_add_f32_e32 v130, v248, v130
	v_add_f32_e32 v130, v249, v130
	v_add_f32_e32 v130, v250, v130
	v_add_f32_e32 v130, v251, v130
	v_add_f32_e32 v130, v252, v130
	v_add_f32_e32 v130, v253, v130
	v_add_f32_e32 v130, v254, v130
	v_add_f32_e32 v130, v255, v130
	v_add_f32_e32 v130, v166, v130
	s_waitcnt lgkmcnt(0)
; DI void a_finishSM(f32x16& p0, f32x16& p1, float alpha, float& l_reg, bf16x8& pa0, bf16x8& pa1, bf16x8& pa2, bf16x8& pa3) {
; #pragma unroll
;   for (int r = 0; r < 16; ++r) p1[r] = __builtin_amdgcn_exp2f(p1[r]);
;   float ps = 0;
; #pragma unroll
;   for (int r = 0; r < 16; ++r) ps += p0[r];
; #pragma unroll
;   for (int r = 0; r < 16; ++r) ps += p1[r];
;   { auto rr = __builtin_amdgcn_permlane32_swap(__float_as_uint(ps), __float_as_uint(ps), false, false);
;     ps = __uint_as_float(rr[0]) + __uint_as_float(rr[1]); }
;   l_reg = l_reg * alpha + ps;
;     ...
;   PK4(p0, 0, pa0); PK4(p0, 8, pa1); PK4(p1, 0, pa2); PK4(p1, 8, pa3);
; DI void pv_sm(f32x16* o, int vb, bf16x8 pa0, bf16x8 pa1, bf16x8 pa2, bf16x8 pa3, f32x16& p0, f32x16& p1, float& m_reg, float& mn, float& alpha) {
;   PV_BLOCK(0)
;   float pm0 = p0[0];
; #pragma unroll
;   for (int r = 1; r < 16; ++r) pm0 = fmaxf(pm0, p0[r]);
;   PV_BLOCK(1)
;   float pmax = pm0;
; #pragma unroll
;   for (int r = 0; r < 16; ++r) pmax = fmaxf(pmax, p1[r]);
;   { auto rr = __builtin_amdgcn_permlane32_swap(__float_as_uint(pmax), __float_as_uint(pmax), false, false);
;     pmax = fmaxf(__uint_as_float(rr[0]), __uint_as_float(rr[1])); }
;   const bool keep = __all(pmax - m_reg <= ATH);
;   mn = keep ? m_reg : fmaxf(m_reg, pmax);
;   alpha = __builtin_amdgcn_exp2f(m_reg - mn);
;   m_reg = mn;
	v_mfma_f32_32x32x16_bf16 v[66:81], v[202:205], v[210:213], v[66:81]
	v_exp_f32_e32 v202, v133
	v_add_f32_e32 v130, v184, v130
	v_add_f32_e32 v130, v146, v130
	v_add_f32_e32 v130, v147, v130
	v_exp_f32_e32 v203, v150
	v_add_f32_e32 v130, v201, v130
	v_exp_f32_e32 v204, v151
	v_add_f32_e32 v130, v202, v130
	v_exp_f32_e32 v205, v154
	v_add_f32_e32 v130, v148, v130
	v_mfma_f32_32x32x16_bf16 v[82:97], v[206:209], v[210:213], v[82:97]
	v_exp_f32_e32 v206, v155
	v_add_f32_e32 v130, v149, v130
	v_add_f32_e32 v130, v203, v130
	v_add_f32_e32 v130, v204, v130
	v_exp_f32_e32 v207, v156
	v_add_f32_e32 v130, v205, v130
	v_exp_f32_e32 v208, v157
	v_add_f32_e32 v130, v206, v130
	v_add_f32_e32 v130, v152, v130
	v_add_f32_e32 v130, v153, v130
	v_add_f32_e32 v130, v207, v130
	v_add_f32_e32 v150, v208, v130
	v_mov_b32_e32 v151, v150
	s_nop 1
	v_permlane32_swap_b32_e32 v150, v151
	v_cvt_pk_bf16_f32 v130, v240, v241
	v_cvt_pk_bf16_f32 v133, v246, v247
	v_cvt_pk_bf16_f32 v154, v248, v249
	v_cvt_pk_bf16_f32 v155, v250, v251
	v_cvt_pk_bf16_f32 v156, v252, v253
	v_cvt_pk_bf16_f32 v157, v254, v255
	v_cvt_pk_bf16_f32 v184, v166, v184
	v_cvt_pk_bf16_f32 v185, v146, v147
	v_cvt_pk_bf16_f32 v186, v201, v202
	v_cvt_pk_bf16_f32 v187, v148, v149
	v_cvt_pk_bf16_f32 v188, v203, v204
	v_cvt_pk_bf16_f32 v189, v205, v206
	v_cvt_pk_bf16_f32 v190, v152, v153
	v_cvt_pk_bf16_f32 v191, v207, v208
	v_permlane32_swap_b32_e32 v130, v132
	v_permlane32_swap_b32_e32 v131, v133
	v_permlane32_swap_b32_e32 v154, v156
	v_permlane32_swap_b32_e32 v155, v157
	v_permlane32_swap_b32_e32 v184, v186
	v_permlane32_swap_b32_e32 v185, v187
	v_permlane32_swap_b32_e32 v188, v190
	v_permlane32_swap_b32_e32 v189, v191
	v_lshl_add_u64 v[146:147], s[84:85], 0, v[142:143]
	v_add_co_u32_e32 v148, vcc, s56, v146
	s_nop 1
	v_addc_co_u32_e32 v149, vcc, 0, v147, vcc
	v_add_co_u32_e32 v152, vcc, s57, v146
	s_nop 1
	v_addc_co_u32_e32 v153, vcc, 0, v147, vcc
	global_load_dwordx4 v[192:195], v[148:149], off offset:256
	global_load_dwordx4 v[196:199], v[148:149], off
	global_load_dwordx4 v[200:203], v[152:153], off offset:256
	global_load_dwordx4 v[204:207], v[152:153], off
	v_lshl_add_u64 v[148:149], s[84:85], 0, v[140:141]
	v_add_co_u32_e32 v152, vcc, s58, v148
	s_nop 1
	v_addc_co_u32_e32 v153, vcc, 0, v149, vcc
	global_load_dwordx4 v[208:211], v[152:153], off
	v_add_u32_e32 v166, s8, v171
	ds_read_b64_tr_b16 v[212:213], v166 offset:0
	ds_read_b64_tr_b16 v[214:215], v166 offset:0x800
	ds_read_b64_tr_b16 v[216:217], v166 offset:0x1000
	ds_read_b64_tr_b16 v[218:219], v166 offset:0x1800
	ds_read_b64_tr_b16 v[220:221], v166 offset:0x2000
	ds_read_b64_tr_b16 v[222:223], v166 offset:0x2800
	ds_read_b64_tr_b16 v[224:225], v166 offset:0x3000
	ds_read_b64_tr_b16 v[226:227], v166 offset:0x3800
	s_waitcnt lgkmcnt(0)
	s_nop 0
	v_mfma_f32_32x32x16_bf16 v[2:17], v[130:133], v[212:215], v[2:17]
	ds_read_b64_tr_b16 v[212:213], v166 offset:0x200
	ds_read_b64_tr_b16 v[214:215], v166 offset:0xa00
	v_max_f32_e32 v152, v67, v67
	v_max_f32_e32 v153, v66, v66
	v_max_f32_e32 v152, v153, v152
	v_max3_f32 v152, v152, v68, v69
	v_max3_f32 v152, v152, v70, v71
	v_mfma_f32_32x32x16_bf16 v[2:17], v[154:157], v[216:219], v[2:17]
	ds_read_b64_tr_b16 v[216:217], v166 offset:0x1200
	ds_read_b64_tr_b16 v[218:219], v166 offset:0x1a00
	v_max3_f32 v152, v152, v72, v73
	v_max3_f32 v152, v152, v74, v75
	v_max3_f32 v152, v152, v76, v77
	v_max3_f32 v152, v152, v78, v79
	v_max3_f32 v152, v152, v80, v81
	v_mfma_f32_32x32x16_bf16 v[2:17], v[184:187], v[220:223], v[2:17]
	ds_read_b64_tr_b16 v[220:221], v166 offset:0x2200
	ds_read_b64_tr_b16 v[222:223], v166 offset:0x2a00
	ds_read_b64_tr_b16 v[228:229], v166 offset:0x3200
	ds_read_b64_tr_b16 v[230:231], v166 offset:0x3a00
	s_waitcnt lgkmcnt(0)
	v_mfma_f32_32x32x16_bf16 v[2:17], v[188:191], v[224:227], v[2:17]
	v_mfma_f32_32x32x16_bf16 v[50:65], v[130:133], v[212:215], v[50:65]
	v_max3_f32 v152, v152, v82, v83
	v_max3_f32 v152, v152, v84, v85
	v_max3_f32 v152, v152, v86, v87
	v_max3_f32 v152, v152, v88, v89
	v_max3_f32 v152, v152, v90, v91
	v_max3_f32 v152, v152, v92, v93
	v_max3_f32 v152, v152, v94, v95
	v_mfma_f32_32x32x16_bf16 v[50:65], v[154:157], v[216:219], v[50:65]
	v_max3_f32 v152, v152, v96, v97
	v_mov_b32_e32 v153, v152
	s_nop 1
	v_permlane32_swap_b32_e32 v152, v153
	v_max_f32_e32 v153, v153, v153
	v_max_f32_e32 v152, v152, v152
	v_max_f32_e32 v152, v152, v153
	v_mfma_f32_32x32x16_bf16 v[50:65], v[184:187], v[220:223], v[50:65]
	ds_read_b64_tr_b16 v[212:213], v166 offset:0x400
	v_sub_f32_e32 v153, v152, v144
	ds_read_b64_tr_b16 v[214:215], v166 offset:0xc00
	v_cmp_ge_f32_e32 vcc, s54, v153
	ds_read_b64_tr_b16 v[216:217], v166 offset:0x1400
	s_cmp_eq_u64 vcc, exec
	v_max_f32_e32 v153, v144, v144
	ds_read_b64_tr_b16 v[218:219], v166 offset:0x1c00
	v_mfma_f32_32x32x16_bf16 v[50:65], v[188:191], v[228:231], v[50:65]
	v_max_f32_e32 v152, v153, v152
	s_cselect_b64 vcc, -1, 0
	ds_read_b64_tr_b16 v[220:221], v166 offset:0x2400
	v_cndmask_b32_e32 v153, v152, v144, vcc
	ds_read_b64_tr_b16 v[222:223], v166 offset:0x2c00
	v_sub_f32_e32 v144, v144, v153
	ds_read_b64_tr_b16 v[224:225], v166 offset:0x3400
	v_exp_f32_e32 v152, v144
	ds_read_b64_tr_b16 v[226:227], v166 offset:0x3c00
	s_waitcnt lgkmcnt(0)
; DI void pv_sm(f32x16* o, int vb, bf16x8 pa0, bf16x8 pa1, bf16x8 pa2, bf16x8 pa3, f32x16& p0, f32x16& p1, float& m_reg, float& mn, float& alpha) {
;   PV_BLOCK(0)
;   float pm0 = p0[0];
; #pragma unroll
;   for (int r = 1; r < 16; ++r) pm0 = fmaxf(pm0, p0[r]);
;   PV_BLOCK(1)
;   float pmax = pm0;
; #pragma unroll
;   for (int r = 0; r < 16; ++r) pmax = fmaxf(pmax, p1[r]);
;   { auto rr = __builtin_amdgcn_permlane32_swap(__float_as_uint(pmax), __float_as_uint(pmax), false, false);
;     pmax = fmaxf(__uint_as_float(rr[0]), __uint_as_float(rr[1])); }
;   const bool keep = __all(pmax - m_reg <= ATH);
;   mn = keep ? m_reg : fmaxf(m_reg, pmax);
;   alpha = __builtin_amdgcn_exp2f(m_reg - mn);
;   m_reg = mn;
;   PV_BLOCK(2)
; #pragma unroll
;   for (int r = 0; r < 16; ++r) { p0[r] = p0[r] - mn; p1[r] = p1[r] - mn; }
;   PV_BLOCK(3)
; #pragma unroll
;   for (int r = 0; r < 16; ++r) p0[r] = __builtin_amdgcn_exp2f(p0[r]);
; }
	v_mfma_f32_32x32x16_bf16 v[34:49], v[130:133], v[212:215], v[34:49]
	ds_read_b64_tr_b16 v[212:213], v166 offset:0x600
	ds_read_b64_tr_b16 v[214:215], v166 offset:0xe00
	v_sub_f32_e32 v66, v66, v153
	v_sub_f32_e32 v67, v67, v153
	v_sub_f32_e32 v68, v68, v153
	v_sub_f32_e32 v69, v69, v153
	v_mfma_f32_32x32x16_bf16 v[34:49], v[154:157], v[216:219], v[34:49]
	ds_read_b64_tr_b16 v[216:217], v166 offset:0x1600
	ds_read_b64_tr_b16 v[218:219], v166 offset:0x1e00
	v_sub_f32_e32 v70, v70, v153
	v_sub_f32_e32 v71, v71, v153
	v_exp_f32_e32 v240, v66
	v_exp_f32_e32 v241, v67
	v_mfma_f32_32x32x16_bf16 v[34:49], v[184:187], v[220:223], v[34:49]
	ds_read_b64_tr_b16 v[220:221], v166 offset:0x2600
	ds_read_b64_tr_b16 v[222:223], v166 offset:0x2e00
	ds_read_b64_tr_b16 v[228:229], v166 offset:0x3600
	ds_read_b64_tr_b16 v[230:231], v166 offset:0x3e00
	v_sub_f32_e32 v72, v72, v153
	v_sub_f32_e32 v73, v73, v153
	v_exp_f32_e32 v242, v68
	v_exp_f32_e32 v243, v69
	s_waitcnt lgkmcnt(0)
	v_mfma_f32_32x32x16_bf16 v[34:49], v[188:191], v[224:227], v[34:49]
	v_sub_f32_e32 v74, v74, v153
	v_sub_f32_e32 v75, v75, v153
	v_exp_f32_e32 v244, v70
	v_exp_f32_e32 v245, v71
	v_mfma_f32_32x32x16_bf16 v[18:33], v[130:133], v[212:215], v[18:33]
	v_sub_f32_e32 v76, v76, v153
	v_sub_f32_e32 v77, v77, v153
	v_exp_f32_e32 v246, v72
	v_exp_f32_e32 v247, v73
	s_add_i32 s9, s6, 0
	v_add_u32_e32 v130, s9, v164
	s_waitcnt vmcnt(0)
	s_waitcnt vmcnt(4)
	ds_write_b128 v130, v[192:195]
	v_add_u32_e32 v130, s9, v165
	s_waitcnt vmcnt(2)
	ds_write_b128 v130, v[200:203]
	v_add_u32_e32 v130, s9, v167
	v_mfma_f32_32x32x16_bf16 v[18:33], v[154:157], v[216:219], v[18:33]
	ds_write_b128 v130, v[196:199] offset:16384
	v_add_u32_e32 v130, s9, v168
	s_waitcnt vmcnt(1)
	ds_write_b128 v130, v[204:207] offset:16384
	v_add_u32_e32 v130, s9, v169
	v_cmp_gt_f32_e32 vcc, 1.0, v152
	s_waitcnt vmcnt(0)
	ds_write_b128 v130, v[208:211] offset:32768
	v_sub_f32_e32 v78, v78, v153
	v_sub_f32_e32 v79, v79, v153
	v_exp_f32_e32 v248, v74
	v_exp_f32_e32 v249, v75
	v_mfma_f32_32x32x16_bf16 v[18:33], v[184:187], v[220:223], v[18:33]
	v_sub_f32_e32 v80, v80, v153
	v_sub_f32_e32 v81, v81, v153
	v_exp_f32_e32 v250, v76
	v_exp_f32_e32 v251, v77
	v_mfma_f32_32x32x16_bf16 v[18:33], v[188:191], v[228:231], v[18:33]
	v_exp_f32_e32 v252, v78
	v_exp_f32_e32 v253, v79
	v_exp_f32_e32 v254, v80
	v_exp_f32_e32 v255, v81
	s_cbranch_vccz .LBB0_669
	s_and_saveexec_b64 s[4:5], s[2:3]
	ds_write_b32 v161, v152 offset:128
	s_or_b64 exec, exec, s[4:5]
	s_waitcnt lgkmcnt(0)
	v_add_u32_e32 v144, v137, v134
	ds_read_b128 v[130:133], v144 offset:224
	ds_read_b128 v[154:157], v144 offset:192
	ds_read_b128 v[184:187], v144 offset:160
	ds_read_b128 v[188:191], v144 offset:128
	s_waitcnt lgkmcnt(3)
	v_pk_mul_f32 v[14:15], v[14:15], v[130:131]
	s_waitcnt lgkmcnt(2)
	v_pk_mul_f32 v[10:11], v[10:11], v[154:155]
	s_waitcnt lgkmcnt(1)
	v_pk_mul_f32 v[6:7], v[6:7], v[184:185]
	v_pk_mul_f32 v[16:17], v[16:17], v[132:133]
	v_pk_mul_f32 v[12:13], v[12:13], v[156:157]
	v_pk_mul_f32 v[8:9], v[8:9], v[186:187]
	s_waitcnt lgkmcnt(0)
	v_pk_mul_f32 v[4:5], v[4:5], v[190:191]
	v_pk_mul_f32 v[2:3], v[2:3], v[188:189]
	v_pk_mul_f32 v[62:63], v[62:63], v[130:131]
	v_pk_mul_f32 v[58:59], v[58:59], v[154:155]
	v_pk_mul_f32 v[54:55], v[54:55], v[184:185]
	v_pk_mul_f32 v[64:65], v[64:65], v[132:133]
	v_pk_mul_f32 v[60:61], v[60:61], v[156:157]
	v_pk_mul_f32 v[56:57], v[56:57], v[186:187]
	v_pk_mul_f32 v[52:53], v[52:53], v[190:191]
	v_pk_mul_f32 v[50:51], v[50:51], v[188:189]
	v_pk_mul_f32 v[46:47], v[46:47], v[130:131]
	v_pk_mul_f32 v[42:43], v[42:43], v[154:155]
	v_pk_mul_f32 v[38:39], v[38:39], v[184:185]
	v_pk_mul_f32 v[48:49], v[48:49], v[132:133]
	v_pk_mul_f32 v[44:45], v[44:45], v[156:157]
	v_pk_mul_f32 v[40:41], v[40:41], v[186:187]
	v_pk_mul_f32 v[36:37], v[36:37], v[190:191]
	v_pk_mul_f32 v[34:35], v[34:35], v[188:189]
	v_pk_mul_f32 v[30:31], v[30:31], v[130:131]
	v_pk_mul_f32 v[26:27], v[26:27], v[154:155]
	v_pk_mul_f32 v[22:23], v[22:23], v[184:185]
	v_pk_mul_f32 v[32:33], v[32:33], v[132:133]
	v_pk_mul_f32 v[28:29], v[28:29], v[156:157]
	v_pk_mul_f32 v[24:25], v[24:25], v[186:187]
	v_pk_mul_f32 v[20:21], v[20:21], v[190:191]
	v_pk_mul_f32 v[18:19], v[18:19], v[188:189]
.LBB0_669:
	s_waitcnt lgkmcnt(0)
	s_barrier
; #define MFMA32(a, b, c) __builtin_amdgcn_mfma_f32_32x32x16_bf16((a), (b), (c), 0, 0, 0)
; DI void a_qkt(f32x16& p0, f32x16& p1, const char* Ks, const char* Ps, const bf16x8* qr, const char* QP, int r32, int hi) {
;   p0 = f32x16{}; p1 = f32x16{};
; #pragma unroll
;   for (int d0 = 0; d0 < 8; ++d0) { const int cb = (d0 * 16 + hi * 8) * 2;
;     bf16x8 b0 = *reinterpret_cast<const bf16x8*>(Ks + KSWZ(r32, cb));
;     bf16x8 b1 = *reinterpret_cast<const bf16x8*>(Ks + KSWZ(32 + r32, cb));
;     p0 = MFMA32(b0, qr[d0], p0);
;     p1 = MFMA32(b1, qr[d0], p1); }
; #pragma unroll
;   for (int d0 = 0; d0 < 4; ++d0) { const int cb = (d0 * 16 + hi * 8) * 2;
;     bf16x8 b0 = *reinterpret_cast<const bf16x8*>(Ps + PSWZ(r32, cb));
;     bf16x8 b1 = *reinterpret_cast<const bf16x8*>(Ps + PSWZ(32 + r32, cb));
;     const bf16x8 qp = *reinterpret_cast<const bf16x8*>(QP + d0 * 1024);
;     p0 = MFMA32(b0, qp, p0);
;     p1 = MFMA32(b1, qp, p1); }
; }
; DI void pv_sm(f32x16* o, int vb, bf16x8 pa0, bf16x8 pa1, bf16x8 pa2, bf16x8 pa3, f32x16& p0, f32x16& p1, float& m_reg, float& mn, float& alpha) {
;     ...
;   for (int r = 0; r < 16; ++r) { p0[r] = p0[r] - mn; p1[r] = p1[r] - mn; }
;   PV_BLOCK(3)
; #pragma unroll
;   for (int r = 0; r < 16; ++r) p0[r] = __builtin_amdgcn_exp2f(p0[r]);
	v_add_u32_e32 v70, s9, v170
	ds_read_b128 v[66:69], v70 offset:16384
	ds_read_b128 v[70:73], v70 offset:24576
	v_add_u32_e32 v154, s9, v172
	ds_read_b128 v[130:133], v154 offset:16384
	ds_read_b128 v[154:157], v154 offset:24576
	v_sub_f32_e32 v144, v82, v153
	v_sub_f32_e32 v188, v83, v153
	v_sub_f32_e32 v189, v84, v153
	v_sub_f32_e32 v190, v85, v153
	v_sub_f32_e32 v191, v86, v153
	v_sub_f32_e32 v192, v87, v153
	v_sub_f32_e32 v193, v88, v153
	v_sub_f32_e32 v194, v89, v153
	v_sub_f32_e32 v195, v90, v153
	v_sub_f32_e32 v196, v91, v153
	v_sub_f32_e32 v197, v92, v153
	v_sub_f32_e32 v198, v93, v153
	v_sub_f32_e32 v199, v94, v153
	v_sub_f32_e32 v200, v95, v153
	v_sub_f32_e32 v201, v96, v153
	v_sub_f32_e32 v202, v97, v153
	v_exp_f32_e32 v144, v144
	s_waitcnt lgkmcnt(3)
	v_mfma_f32_32x32x16_bf16 v[82:97], v[66:69], v[114:117], 0
	v_exp_f32_e32 v192, v192
	v_exp_f32_e32 v193, v193
	v_exp_f32_e32 v194, v194
	v_exp_f32_e32 v195, v195
	v_exp_f32_e32 v196, v196
	v_exp_f32_e32 v197, v197
	v_exp_f32_e32 v198, v198
	s_waitcnt lgkmcnt(2)
	v_mfma_f32_32x32x16_bf16 v[66:81], v[70:73], v[114:117], 0
	v_exp_f32_e32 v199, v199
	v_exp_f32_e32 v200, v200
	v_exp_f32_e32 v201, v201
	v_exp_f32_e32 v202, v202
	s_waitcnt lgkmcnt(1)
	v_mfma_f32_32x32x16_bf16 v[82:97], v[130:133], v[118:121], v[82:97]
	s_waitcnt lgkmcnt(0)
	v_mfma_f32_32x32x16_bf16 v[66:81], v[154:157], v[118:121], v[66:81]
	v_add_u32_e32 v154, s9, v173
	ds_read_b128 v[130:133], v154 offset:16384
	ds_read_b128 v[154:157], v154 offset:24576
	s_waitcnt lgkmcnt(1)
	v_mfma_f32_32x32x16_bf16 v[82:97], v[130:133], v[126:129], v[82:97]
	s_waitcnt lgkmcnt(0)
	v_mfma_f32_32x32x16_bf16 v[66:81], v[154:157], v[126:129], v[66:81]
	v_add_u32_e32 v154, s9, v174
	ds_read_b128 v[130:133], v154 offset:16384
	ds_read_b128 v[154:157], v154 offset:24576
	s_waitcnt lgkmcnt(1)
	v_mfma_f32_32x32x16_bf16 v[82:97], v[130:133], v[122:125], v[82:97]
	s_waitcnt lgkmcnt(0)
	v_mfma_f32_32x32x16_bf16 v[66:81], v[154:157], v[122:125], v[66:81]
	v_add_u32_e32 v154, s9, v175
	ds_read_b128 v[130:133], v154 offset:16384
	ds_read_b128 v[154:157], v154 offset:24576
	s_waitcnt lgkmcnt(1)
	v_mfma_f32_32x32x16_bf16 v[82:97], v[130:133], v[110:113], v[82:97]
	s_waitcnt lgkmcnt(0)
	v_mfma_f32_32x32x16_bf16 v[66:81], v[154:157], v[110:113], v[66:81]
	v_add_u32_e32 v154, s9, v176
	ds_read_b128 v[130:133], v154 offset:16384
	ds_read_b128 v[154:157], v154 offset:24576
	s_waitcnt lgkmcnt(1)
	v_mfma_f32_32x32x16_bf16 v[82:97], v[130:133], v[106:109], v[82:97]
	s_waitcnt lgkmcnt(0)
	v_mfma_f32_32x32x16_bf16 v[66:81], v[154:157], v[106:109], v[66:81]
	v_add_u32_e32 v154, s9, v177
	ds_read_b128 v[130:133], v154 offset:16384
	ds_read_b128 v[154:157], v154 offset:24576
	s_waitcnt lgkmcnt(1)
	v_mfma_f32_32x32x16_bf16 v[82:97], v[130:133], v[102:105], v[82:97]
	s_waitcnt lgkmcnt(0)
	v_mfma_f32_32x32x16_bf16 v[66:81], v[154:157], v[102:105], v[66:81]
	v_add_u32_e32 v154, s9, v178
	ds_read_b128 v[130:133], v154 offset:16384
	ds_read_b128 v[154:157], v154 offset:24576
	s_waitcnt lgkmcnt(1)
	v_mfma_f32_32x32x16_bf16 v[82:97], v[130:133], v[98:101], v[82:97]
	s_waitcnt lgkmcnt(0)
	v_mfma_f32_32x32x16_bf16 v[66:81], v[154:157], v[98:101], v[66:81]
	v_add_u32_e32 v154, s9, v179
	ds_read_b128 v[130:133], v154 offset:32768
	ds_read_b128 v[154:157], v154 offset:36864
	ds_read_b128 v[184:187], v163
	s_waitcnt lgkmcnt(0)
	v_mfma_f32_32x32x16_bf16 v[82:97], v[130:133], v[184:187], v[82:97]
	v_mfma_f32_32x32x16_bf16 v[66:81], v[154:157], v[184:187], v[66:81]
	v_add_u32_e32 v154, s9, v180
	ds_read_b128 v[130:133], v154 offset:32768
	ds_read_b128 v[154:157], v154 offset:36864
	ds_read_b128 v[184:187], v163 offset:1024
	s_waitcnt lgkmcnt(0)
	v_mfma_f32_32x32x16_bf16 v[82:97], v[130:133], v[184:187], v[82:97]
	v_mfma_f32_32x32x16_bf16 v[66:81], v[154:157], v[184:187], v[66:81]
	v_add_u32_e32 v154, s9, v181
	ds_read_b128 v[130:133], v154 offset:32768
	ds_read_b128 v[154:157], v154 offset:36864
	ds_read_b128 v[184:187], v163 offset:2048
	s_waitcnt lgkmcnt(0)
	v_mfma_f32_32x32x16_bf16 v[82:97], v[130:133], v[184:187], v[82:97]
	v_mfma_f32_32x32x16_bf16 v[66:81], v[154:157], v[184:187], v[66:81]
	v_add_u32_e32 v154, s9, v182
	ds_read_b128 v[130:133], v154 offset:32768
	ds_read_b128 v[154:157], v154 offset:36864
	ds_read_b128 v[184:187], v163 offset:3072
	s_waitcnt lgkmcnt(0)
; DI void a_finishSM(f32x16& p0, f32x16& p1, float alpha, float& l_reg, bf16x8& pa0, bf16x8& pa1, bf16x8& pa2, bf16x8& pa3) {
; #pragma unroll
;   for (int r = 0; r < 16; ++r) p1[r] = __builtin_amdgcn_exp2f(p1[r]);
;   float ps = 0;
; #pragma unroll
;   for (int r = 0; r < 16; ++r) ps += p0[r];
; #pragma unroll
;   for (int r = 0; r < 16; ++r) ps += p1[r];
;   { auto rr = __builtin_amdgcn_permlane32_swap(__float_as_uint(ps), __float_as_uint(ps), false, false);
;     ps = __uint_as_float(rr[0]) + __uint_as_float(rr[1]); }
;   l_reg = l_reg * alpha + ps;
;     ...
;   PK4(p0, 0, pa0); PK4(p0, 8, pa1); PK4(p1, 0, pa2); PK4(p1, 8, pa3);
; DI void pv_sm(f32x16* o, int vb, bf16x8 pa0, bf16x8 pa1, bf16x8 pa2, bf16x8 pa3, f32x16& p0, f32x16& p1, float& m_reg, float& mn, float& alpha) {
;   PV_BLOCK(0)
;   float pm0 = p0[0];
; #pragma unroll
;   for (int r = 1; r < 16; ++r) pm0 = fmaxf(pm0, p0[r]);
;   PV_BLOCK(1)
;   float pmax = pm0;
; #pragma unroll
;   for (int r = 0; r < 16; ++r) pmax = fmaxf(pmax, p1[r]);
;   { auto rr = __builtin_amdgcn_permlane32_swap(__float_as_uint(pmax), __float_as_uint(pmax), false, false);
;     pmax = fmaxf(__uint_as_float(rr[0]), __uint_as_float(rr[1])); }
;   const bool keep = __all(pmax - m_reg <= ATH);
;   mn = keep ? m_reg : fmaxf(m_reg, pmax);
;   alpha = __builtin_amdgcn_exp2f(m_reg - mn);
;   m_reg = mn;
	v_mfma_f32_32x32x16_bf16 v[82:97], v[130:133], v[184:187], v[82:97]
	v_add_f32_e32 v130, 0, v240
	v_add_f32_e32 v130, v241, v130
	v_add_f32_e32 v130, v242, v130
	v_add_f32_e32 v130, v243, v130
	v_add_f32_e32 v130, v244, v130
	v_add_f32_e32 v130, v245, v130
	v_add_f32_e32 v130, v246, v130
	v_add_f32_e32 v130, v247, v130
	v_add_f32_e32 v130, v248, v130
	v_add_f32_e32 v130, v249, v130
	v_add_f32_e32 v130, v250, v130
	v_add_f32_e32 v130, v251, v130
	v_add_f32_e32 v130, v252, v130
	v_mfma_f32_32x32x16_bf16 v[66:81], v[154:157], v[184:187], v[66:81]
	v_exp_f32_e32 v156, v188
	v_add_f32_e32 v130, v253, v130
	v_exp_f32_e32 v157, v189
	v_add_f32_e32 v130, v254, v130
	v_exp_f32_e32 v184, v190
	v_add_f32_e32 v130, v255, v130
	v_exp_f32_e32 v185, v191
	v_add_f32_e32 v130, v144, v130
	v_add_f32_e32 v130, v156, v130
	v_add_f32_e32 v130, v157, v130
	v_add_f32_e32 v130, v184, v130
	v_add_f32_e32 v130, v185, v130
	v_add_f32_e32 v130, v192, v130
	v_add_f32_e32 v130, v193, v130
	v_add_f32_e32 v130, v194, v130
	v_add_f32_e32 v130, v195, v130
	v_add_f32_e32 v130, v196, v130
	v_add_f32_e32 v130, v197, v130
	v_add_f32_e32 v130, v198, v130
	v_add_f32_e32 v130, v199, v130
	v_add_f32_e32 v130, v200, v130
	v_add_f32_e32 v130, v201, v130
	v_add_f32_e32 v154, v202, v130
	v_mov_b32_e32 v155, v154
	s_nop 1
	v_permlane32_swap_b32_e32 v154, v155
	v_cvt_pk_bf16_f32 v130, v240, v241
	v_cvt_pk_bf16_f32 v131, v242, v243
	v_cvt_pk_bf16_f32 v132, v244, v245
	v_cvt_pk_bf16_f32 v133, v246, v247
	v_cvt_pk_bf16_f32 v186, v248, v249
	v_cvt_pk_bf16_f32 v187, v250, v251
	v_cvt_pk_bf16_f32 v188, v252, v253
	v_cvt_pk_bf16_f32 v189, v254, v255
	v_cvt_pk_bf16_f32 v190, v144, v156
	v_cvt_pk_bf16_f32 v191, v157, v184
	v_cvt_pk_bf16_f32 v192, v185, v192
	v_cvt_pk_bf16_f32 v193, v193, v194
	v_cvt_pk_bf16_f32 v194, v195, v196
	v_cvt_pk_bf16_f32 v195, v197, v198
	v_cvt_pk_bf16_f32 v196, v199, v200
	v_cvt_pk_bf16_f32 v197, v201, v202
	v_permlane32_swap_b32_e32 v130, v132
	v_permlane32_swap_b32_e32 v131, v133
	v_permlane32_swap_b32_e32 v186, v188
	v_permlane32_swap_b32_e32 v187, v189
	v_permlane32_swap_b32_e32 v190, v192
	v_permlane32_swap_b32_e32 v191, v193
	v_permlane32_swap_b32_e32 v194, v196
	v_permlane32_swap_b32_e32 v195, v197
	v_add_co_u32_e32 v156, vcc, s59, v146
	s_nop 1
	v_addc_co_u32_e32 v157, vcc, 0, v147, vcc
	v_add_co_u32_e32 v146, vcc, s60, v146
	s_nop 1
	v_addc_co_u32_e32 v147, vcc, 0, v147, vcc
	global_load_dwordx4 v[198:201], v[156:157], off offset:256
	global_load_dwordx4 v[202:205], v[156:157], off
	global_load_dwordx4 v[206:209], v[146:147], off offset:256
	global_load_dwordx4 v[210:213], v[146:147], off
	v_add_co_u32_e32 v146, vcc, s61, v148
	s_nop 1
	v_addc_co_u32_e32 v147, vcc, 0, v149, vcc
	global_load_dwordx4 v[146:149], v[146:147], off
	v_add_u32_e32 v156, s7, v171
	ds_read_b64_tr_b16 v[214:215], v156 offset:0
	ds_read_b64_tr_b16 v[216:217], v156 offset:0x800
	ds_read_b64_tr_b16 v[218:219], v156 offset:0x1000
	ds_read_b64_tr_b16 v[220:221], v156 offset:0x1800
	ds_read_b64_tr_b16 v[222:223], v156 offset:0x2000
	ds_read_b64_tr_b16 v[224:225], v156 offset:0x2800
	ds_read_b64_tr_b16 v[226:227], v156 offset:0x3000
	ds_read_b64_tr_b16 v[228:229], v156 offset:0x3800
	s_waitcnt lgkmcnt(0)
	s_nop 0
	v_mfma_f32_32x32x16_bf16 v[2:17], v[130:133], v[214:217], v[2:17]
	ds_read_b64_tr_b16 v[214:215], v156 offset:0x200
	ds_read_b64_tr_b16 v[216:217], v156 offset:0xa00
	v_max_f32_e32 v144, v83, v83
	v_max_f32_e32 v157, v82, v82
	v_max_f32_e32 v144, v157, v144
	v_max3_f32 v144, v144, v84, v85
	v_max3_f32 v144, v144, v86, v87
	v_mfma_f32_32x32x16_bf16 v[2:17], v[186:189], v[218:221], v[2:17]
	ds_read_b64_tr_b16 v[218:219], v156 offset:0x1200
	ds_read_b64_tr_b16 v[220:221], v156 offset:0x1a00
	v_max3_f32 v144, v144, v88, v89
	v_max3_f32 v144, v144, v90, v91
	v_max3_f32 v144, v144, v92, v93
	v_max3_f32 v144, v144, v94, v95
	v_max3_f32 v144, v144, v96, v97
	v_mfma_f32_32x32x16_bf16 v[2:17], v[190:193], v[222:225], v[2:17]
	ds_read_b64_tr_b16 v[222:223], v156 offset:0x2200
	ds_read_b64_tr_b16 v[224:225], v156 offset:0x2a00
	ds_read_b64_tr_b16 v[230:231], v156 offset:0x3200
	ds_read_b64_tr_b16 v[232:233], v156 offset:0x3a00
	s_waitcnt lgkmcnt(0)
	v_mfma_f32_32x32x16_bf16 v[2:17], v[194:197], v[226:229], v[2:17]
	v_mfma_f32_32x32x16_bf16 v[50:65], v[130:133], v[214:217], v[50:65]
	v_max3_f32 v144, v144, v66, v67
	v_max3_f32 v144, v144, v68, v69
	v_max3_f32 v144, v144, v70, v71
	v_max3_f32 v144, v144, v72, v73
	v_max3_f32 v144, v144, v74, v75
	v_max3_f32 v144, v144, v76, v77
	v_max3_f32 v144, v144, v78, v79
	v_mfma_f32_32x32x16_bf16 v[50:65], v[186:189], v[218:221], v[50:65]
	v_max3_f32 v144, v144, v80, v81
	v_mov_b32_e32 v157, v144
	s_nop 1
	v_permlane32_swap_b32_e32 v144, v157
	v_max_f32_e32 v157, v157, v157
	v_max_f32_e32 v144, v144, v144
	v_max_f32_e32 v144, v144, v157
	v_mfma_f32_32x32x16_bf16 v[50:65], v[190:193], v[222:225], v[50:65]
	ds_read_b64_tr_b16 v[214:215], v156 offset:0x400
	v_sub_f32_e32 v157, v144, v153
	ds_read_b64_tr_b16 v[216:217], v156 offset:0xc00
	v_cmp_ge_f32_e32 vcc, s54, v157
	ds_read_b64_tr_b16 v[218:219], v156 offset:0x1400
	s_cmp_eq_u64 vcc, exec
	v_max_f32_e32 v157, v153, v153
	ds_read_b64_tr_b16 v[220:221], v156 offset:0x1c00
	v_mfma_f32_32x32x16_bf16 v[50:65], v[194:197], v[230:233], v[50:65]
	v_max_f32_e32 v144, v157, v144
	s_cselect_b64 vcc, -1, 0
	ds_read_b64_tr_b16 v[222:223], v156 offset:0x2400
	v_cndmask_b32_e32 v144, v144, v153, vcc
	ds_read_b64_tr_b16 v[224:225], v156 offset:0x2c00
	v_sub_f32_e32 v153, v153, v144
	ds_read_b64_tr_b16 v[226:227], v156 offset:0x3400
	v_exp_f32_e32 v184, v153
	ds_read_b64_tr_b16 v[228:229], v156 offset:0x3c00
	s_waitcnt lgkmcnt(0)
; #define SBAR() __builtin_amdgcn_sched_barrier(0)
; DI void pv_sm(f32x16* o, int vb, bf16x8 pa0, bf16x8 pa1, bf16x8 pa2, bf16x8 pa3, f32x16& p0, f32x16& p1, float& m_reg, float& mn, float& alpha) {
;   PV_BLOCK(0)
;   float pm0 = p0[0];
; #pragma unroll
;   for (int r = 1; r < 16; ++r) pm0 = fmaxf(pm0, p0[r]);
;   PV_BLOCK(1)
;   float pmax = pm0;
; #pragma unroll
;   for (int r = 0; r < 16; ++r) pmax = fmaxf(pmax, p1[r]);
;   { auto rr = __builtin_amdgcn_permlane32_swap(__float_as_uint(pmax), __float_as_uint(pmax), false, false);
;     pmax = fmaxf(__uint_as_float(rr[0]), __uint_as_float(rr[1])); }
;   const bool keep = __all(pmax - m_reg <= ATH);
;   mn = keep ? m_reg : fmaxf(m_reg, pmax);
;   alpha = __builtin_amdgcn_exp2f(m_reg - mn);
;   m_reg = mn;
;   PV_BLOCK(2)
; #pragma unroll
;   for (int r = 0; r < 16; ++r) { p0[r] = p0[r] - mn; p1[r] = p1[r] - mn; }
;   PV_BLOCK(3)
; #pragma unroll
;   for (int r = 0; r < 16; ++r) p0[r] = __builtin_amdgcn_exp2f(p0[r]);
; }
; DI void attn_unit(const bf16_t* __restrict__ Qb, const bf16_t* __restrict__ Kh, const bf16_t* __restrict__ Vh, const bf16_t* __restrict__ Ph,
;                   bf16_t* __restrict__ Ob, int seq, float* __restrict__ lse_out, char* lds) {
;     ...
;   f32x16 pA0, pA1, pB0, pB1; float mnA, mnB, alA, alB; bf16x8 pa0, pa1, pa2, pa3; const int NT = seq / 64;
;   SLOAD(0); SWAIT(); SWRITE(0); __syncthreads();
;   a_qkt(pA0, pA1, lds + A_KO, lds + A_PO, qr, QP, r32, hi); a_partialSM(pA0, pA1, m_reg, mnA, alA);
;   SLOAD(64);
;   SWAIT(); SWRITE(A_STG); __syncthreads();
;   int sV = 0, sK = A_STG, sW = 2 * A_STG;
;   for (int j = 1; j + 1 < NT; j += 2) {
;     SBAR(); a_qkt(pB0, pB1, lds + sK + A_KO, lds + sK + A_PO, qr, QP, r32, hi);
;     a_finishSM(pA0, pA1, alA, l_reg, pa0, pa1, pa2, pa3); SBAR();
;     SLOAD((j + 1) * 64); SBAR();
;     pv_sm(o, vb0 + sV, pa0, pa1, pa2, pa3, pB0, pB1, m_reg, mnB, alB);
;     SWAIT(); SWRITE(sW);
;     RESC(alB); __syncthreads();
;     { const int t_ = sV; sV = sK; sK = sW; sW = t_; }
;     SBAR(); a_qkt(pA0, pA1, lds + sK + A_KO, lds + sK + A_PO, qr, QP, r32, hi);
;     a_finishSM(pB0, pB1, alB, l_reg, pa0, pa1, pa2, pa3); SBAR();
;     SLOAD((j + 2) * 64); SBAR();
;     pv_sm(o, vb0 + sV, pa0, pa1, pa2, pa3, pA0, pA1, m_reg, mnA, alA);
;     SWAIT(); SWRITE(sW);
;     RESC(alA); __syncthreads();
;     { const int t_ = sV; sV = sK; sK = sW; sW = t_; }
	v_mfma_f32_32x32x16_bf16 v[34:49], v[130:133], v[214:217], v[34:49]
	ds_read_b64_tr_b16 v[214:215], v156 offset:0x600
	ds_read_b64_tr_b16 v[216:217], v156 offset:0xe00
	v_sub_f32_e32 v82, v82, v144
	v_sub_f32_e32 v83, v83, v144
	v_sub_f32_e32 v84, v84, v144
	v_sub_f32_e32 v85, v85, v144
	v_mfma_f32_32x32x16_bf16 v[34:49], v[186:189], v[218:221], v[34:49]
	ds_read_b64_tr_b16 v[218:219], v156 offset:0x1600
	ds_read_b64_tr_b16 v[220:221], v156 offset:0x1e00
	v_sub_f32_e32 v86, v86, v144
	v_sub_f32_e32 v87, v87, v144
	v_exp_f32_e32 v240, v82
	v_exp_f32_e32 v241, v83
	v_mfma_f32_32x32x16_bf16 v[34:49], v[190:193], v[222:225], v[34:49]
	ds_read_b64_tr_b16 v[222:223], v156 offset:0x2600
	ds_read_b64_tr_b16 v[224:225], v156 offset:0x2e00
	ds_read_b64_tr_b16 v[230:231], v156 offset:0x3600
	ds_read_b64_tr_b16 v[232:233], v156 offset:0x3e00
	v_sub_f32_e32 v88, v88, v144
	v_sub_f32_e32 v89, v89, v144
	v_exp_f32_e32 v242, v84
	v_exp_f32_e32 v243, v85
	s_waitcnt lgkmcnt(0)
	v_mfma_f32_32x32x16_bf16 v[34:49], v[194:197], v[226:229], v[34:49]
	v_sub_f32_e32 v90, v90, v144
	v_sub_f32_e32 v91, v91, v144
	v_exp_f32_e32 v244, v86
	v_exp_f32_e32 v245, v87
	v_mfma_f32_32x32x16_bf16 v[18:33], v[130:133], v[214:217], v[18:33]
	v_sub_f32_e32 v92, v92, v144
	v_sub_f32_e32 v93, v93, v144
	v_exp_f32_e32 v246, v88
	v_exp_f32_e32 v247, v89
	s_add_i32 s9, s8, 0
	v_add_u32_e32 v130, s9, v164
	s_waitcnt vmcnt(0)
	s_waitcnt vmcnt(4)
	ds_write_b128 v130, v[198:201]
	v_add_u32_e32 v130, s9, v165
	s_waitcnt vmcnt(2)
	ds_write_b128 v130, v[206:209]
	v_add_u32_e32 v130, s9, v167
	v_mfma_f32_32x32x16_bf16 v[18:33], v[186:189], v[218:221], v[18:33]
	ds_write_b128 v130, v[202:205] offset:16384
	v_add_u32_e32 v130, s9, v168
	s_waitcnt vmcnt(1)
	ds_write_b128 v130, v[210:213] offset:16384
	v_add_u32_e32 v130, s9, v169
	v_cmp_gt_f32_e32 vcc, 1.0, v184
	s_waitcnt vmcnt(0)
	ds_write_b128 v130, v[146:149] offset:32768
	v_sub_f32_e32 v94, v94, v144
	v_sub_f32_e32 v95, v95, v144
	v_exp_f32_e32 v248, v90
	v_exp_f32_e32 v249, v91
	v_mfma_f32_32x32x16_bf16 v[18:33], v[190:193], v[222:225], v[18:33]
	v_sub_f32_e32 v96, v96, v144
	v_sub_f32_e32 v97, v97, v144
	v_exp_f32_e32 v250, v92
	v_exp_f32_e32 v251, v93
	v_mfma_f32_32x32x16_bf16 v[18:33], v[194:197], v[230:233], v[18:33]
	v_exp_f32_e32 v252, v94
	v_exp_f32_e32 v253, v95
	v_exp_f32_e32 v254, v96
	v_exp_f32_e32 v255, v97
	s_cbranch_vccz .LBB0_673
	s_and_saveexec_b64 s[4:5], s[2:3]
	ds_write_b32 v161, v184 offset:128
	s_or_b64 exec, exec, s[4:5]
	s_waitcnt lgkmcnt(0)
	v_add_u32_e32 v153, v137, v134
	ds_read_b128 v[130:133], v153 offset:224
	ds_read_b128 v[146:149], v153 offset:192
	ds_read_b128 v[186:189], v153 offset:160
	ds_read_b128 v[190:193], v153 offset:128
	s_waitcnt lgkmcnt(3)
	v_pk_mul_f32 v[14:15], v[14:15], v[130:131]
	s_waitcnt lgkmcnt(2)
	v_pk_mul_f32 v[10:11], v[10:11], v[146:147]
	s_waitcnt lgkmcnt(1)
	v_pk_mul_f32 v[6:7], v[6:7], v[186:187]
	v_pk_mul_f32 v[16:17], v[16:17], v[132:133]
	v_pk_mul_f32 v[12:13], v[12:13], v[148:149]
	v_pk_mul_f32 v[8:9], v[8:9], v[188:189]
	s_waitcnt lgkmcnt(0)
	v_pk_mul_f32 v[4:5], v[4:5], v[192:193]
	v_pk_mul_f32 v[2:3], v[2:3], v[190:191]
	v_pk_mul_f32 v[62:63], v[62:63], v[130:131]
	v_pk_mul_f32 v[58:59], v[58:59], v[146:147]
	v_pk_mul_f32 v[54:55], v[54:55], v[186:187]
	v_pk_mul_f32 v[64:65], v[64:65], v[132:133]
	v_pk_mul_f32 v[60:61], v[60:61], v[148:149]
	v_pk_mul_f32 v[56:57], v[56:57], v[188:189]
	v_pk_mul_f32 v[52:53], v[52:53], v[192:193]
	v_pk_mul_f32 v[50:51], v[50:51], v[190:191]
	v_pk_mul_f32 v[46:47], v[46:47], v[130:131]
	v_pk_mul_f32 v[42:43], v[42:43], v[146:147]
	v_pk_mul_f32 v[38:39], v[38:39], v[186:187]
	v_pk_mul_f32 v[48:49], v[48:49], v[132:133]
	v_pk_mul_f32 v[44:45], v[44:45], v[148:149]
	v_pk_mul_f32 v[40:41], v[40:41], v[188:189]
	v_pk_mul_f32 v[36:37], v[36:37], v[192:193]
	v_pk_mul_f32 v[34:35], v[34:35], v[190:191]
	v_pk_mul_f32 v[30:31], v[30:31], v[130:131]
	v_pk_mul_f32 v[26:27], v[26:27], v[146:147]
	v_pk_mul_f32 v[22:23], v[22:23], v[186:187]
	v_pk_mul_f32 v[32:33], v[32:33], v[132:133]
	v_pk_mul_f32 v[28:29], v[28:29], v[148:149]
	v_pk_mul_f32 v[24:25], v[24:25], v[188:189]
	v_pk_mul_f32 v[20:21], v[20:21], v[192:193]
	v_pk_mul_f32 v[18:19], v[18:19], v[190:191]
.LBB0_673:
	v_add_f32_e32 v130, v150, v151
	v_fmac_f32_e32 v130, v183, v162
	v_add_f32_e32 v162, v154, v155
	v_fmac_f32_e32 v162, v130, v152
	v_pk_add_f32 v[130:131], v[66:67], v[144:145] op_sel_hi:[1,0] neg_lo:[0,1] neg_hi:[0,1]
	v_pk_add_f32 v[146:147], v[68:69], v[144:145] op_sel_hi:[1,0] neg_lo:[0,1] neg_hi:[0,1]
	v_pk_add_f32 v[132:133], v[70:71], v[144:145] op_sel_hi:[1,0] neg_lo:[0,1] neg_hi:[0,1]
	v_pk_add_f32 v[148:149], v[72:73], v[144:145] op_sel_hi:[1,0] neg_lo:[0,1] neg_hi:[0,1]
	v_pk_add_f32 v[150:151], v[74:75], v[144:145] op_sel_hi:[1,0] neg_lo:[0,1] neg_hi:[0,1]
	v_pk_add_f32 v[154:155], v[76:77], v[144:145] op_sel_hi:[1,0] neg_lo:[0,1] neg_hi:[0,1]
	v_pk_add_f32 v[152:153], v[78:79], v[144:145] op_sel_hi:[1,0] neg_lo:[0,1] neg_hi:[0,1]
	s_add_i32 s66, s66, 2
	v_pk_add_f32 v[156:157], v[80:81], v[144:145] op_sel_hi:[1,0] neg_lo:[0,1] neg_hi:[0,1]
	v_lshl_add_u64 v[140:141], v[140:141], 0, s[22:23]
	s_cmp_ge_u32 s66, s53
	v_lshl_add_u64 v[142:143], v[142:143], 0, s[24:25]
	s_waitcnt lgkmcnt(0)
	s_barrier
	s_cbranch_scc1 .LBB0_675
	s_mov_b32 s4, s6
	s_mov_b32 s6, s7
	s_mov_b32 s7, s8
	v_mov_b32_e32 v183, v184
	s_branch .LBB0_665
; #define MFMA32(a, b, c) __builtin_amdgcn_mfma_f32_32x32x16_bf16((a), (b), (c), 0, 0, 0)
; #define SBAR() __builtin_amdgcn_sched_barrier(0)
; DI void a_finishSM(f32x16& p0, f32x16& p1, float alpha, float& l_reg, bf16x8& pa0, bf16x8& pa1, bf16x8& pa2, bf16x8& pa3) {
; #pragma unroll
;   for (int r = 0; r < 16; ++r) p1[r] = __builtin_amdgcn_exp2f(p1[r]);
;   float ps = 0;
; #pragma unroll
;   for (int r = 0; r < 16; ++r) ps += p0[r];
; #pragma unroll
;   for (int r = 0; r < 16; ++r) ps += p1[r];
;   { auto rr = __builtin_amdgcn_permlane32_swap(__float_as_uint(ps), __float_as_uint(ps), false, false);
;     ps = __uint_as_float(rr[0]) + __uint_as_float(rr[1]); }
;   l_reg = l_reg * alpha + ps;
;     ...
;   PK4(p0, 0, pa0); PK4(p0, 8, pa1); PK4(p1, 0, pa2); PK4(p1, 8, pa3);
;     ...
; }
; DI void a_qkt(f32x16& p0, f32x16& p1, const char* Ks, const char* Ps, const bf16x8* qr, const char* QP, int r32, int hi) {
;   p0 = f32x16{}; p1 = f32x16{};
; #pragma unroll
;   for (int d0 = 0; d0 < 8; ++d0) { const int cb = (d0 * 16 + hi * 8) * 2;
;     bf16x8 b0 = *reinterpret_cast<const bf16x8*>(Ks + KSWZ(r32, cb));
;     bf16x8 b1 = *reinterpret_cast<const bf16x8*>(Ks + KSWZ(32 + r32, cb));
;     p0 = MFMA32(b0, qr[d0], p0);
;     p1 = MFMA32(b1, qr[d0], p1); }
; #pragma unroll
;   for (int d0 = 0; d0 < 4; ++d0) { const int cb = (d0 * 16 + hi * 8) * 2;
;     bf16x8 b0 = *reinterpret_cast<const bf16x8*>(Ps + PSWZ(r32, cb));
;     bf16x8 b1 = *reinterpret_cast<const bf16x8*>(Ps + PSWZ(32 + r32, cb));
;     const bf16x8 qp = *reinterpret_cast<const bf16x8*>(QP + d0 * 1024);
;     p0 = MFMA32(b0, qp, p0);
;     p1 = MFMA32(b1, qp, p1); }
; }
; DI void attn_unit(const bf16_t* __restrict__ Qb, const bf16_t* __restrict__ Kh, const bf16_t* __restrict__ Vh, const bf16_t* __restrict__ Ph,
;                   bf16_t* __restrict__ Ob, int seq, float* __restrict__ lse_out, char* lds) {
;     ...
;   SBAR(); a_qkt(pB0, pB1, lds + sK + A_KO, lds + sK + A_PO, qr, QP, r32, hi);
;   a_finishSM(pA0, pA1, alA, l_reg, pa0, pa1, pa2, pa3); SBAR();
.LBB0_675:
	v_mov_b32_e32 v191, v240
	v_mov_b32_e32 v192, v241
	v_mov_b32_e32 v194, v242
	v_mov_b32_e32 v196, v243
	v_mov_b32_e32 v198, v244
	v_mov_b32_e32 v200, v245
	v_mov_b32_e32 v197, v246
	v_mov_b32_e32 v199, v247
	v_mov_b32_e32 v185, v248
	v_mov_b32_e32 v186, v249
	v_mov_b32_e32 v188, v250
	v_mov_b32_e32 v190, v251
	v_mov_b32_e32 v187, v252
	v_mov_b32_e32 v189, v253
	v_mov_b32_e32 v193, v254
	v_mov_b32_e32 v195, v255
	v_add_u32_e32 v70, s9, v170
	ds_read_b128 v[66:69], v70 offset:16384
	ds_read_b128 v[70:73], v70 offset:24576
	v_add_u32_e32 v140, s9, v172
	v_add_u32_e32 v164, s9, v178
	v_exp_f32_e32 v130, v130
	s_waitcnt lgkmcnt(1)
	v_mfma_f32_32x32x16_bf16 v[82:97], v[66:69], v[114:117], 0
	v_exp_f32_e32 v131, v131
	v_exp_f32_e32 v146, v146
	v_exp_f32_e32 v147, v147
	v_exp_f32_e32 v132, v132
	s_waitcnt lgkmcnt(0)
	v_mfma_f32_32x32x16_bf16 v[66:81], v[70:73], v[114:117], 0
	ds_read_b128 v[114:117], v140 offset:16384
	ds_read_b128 v[140:143], v140 offset:24576
	s_waitcnt lgkmcnt(1)
	v_mfma_f32_32x32x16_bf16 v[82:97], v[114:117], v[118:121], v[82:97]
	s_waitcnt lgkmcnt(0)
	v_mfma_f32_32x32x16_bf16 v[66:81], v[140:143], v[118:121], v[66:81]
	v_add_u32_e32 v118, s9, v173
	ds_read_b128 v[114:117], v118 offset:16384
	ds_read_b128 v[118:121], v118 offset:24576
	v_add_u32_e32 v140, s9, v177
	s_waitcnt lgkmcnt(1)
	v_mfma_f32_32x32x16_bf16 v[82:97], v[114:117], v[126:129], v[82:97]
	s_waitcnt lgkmcnt(0)
	v_mfma_f32_32x32x16_bf16 v[66:81], v[118:121], v[126:129], v[66:81]
	v_add_u32_e32 v118, s9, v174
	ds_read_b128 v[114:117], v118 offset:16384
	ds_read_b128 v[118:121], v118 offset:24576
	s_waitcnt lgkmcnt(1)
	v_mfma_f32_32x32x16_bf16 v[82:97], v[114:117], v[122:125], v[82:97]
	s_waitcnt lgkmcnt(0)
	v_mfma_f32_32x32x16_bf16 v[66:81], v[118:121], v[122:125], v[66:81]
	v_add_u32_e32 v118, s9, v175
	ds_read_b128 v[114:117], v118 offset:16384
	ds_read_b128 v[118:121], v118 offset:24576
	v_add_u32_e32 v122, s9, v176
	s_waitcnt lgkmcnt(1)
	v_mfma_f32_32x32x16_bf16 v[82:97], v[114:117], v[110:113], v[82:97]
	ds_read_b128 v[114:117], v122 offset:16384
	ds_read_b128 v[122:125], v122 offset:24576
	ds_read_b128 v[126:129], v140 offset:16384
	ds_read_b128 v[140:143], v140 offset:24576
	s_waitcnt lgkmcnt(4)
	v_mfma_f32_32x32x16_bf16 v[66:81], v[118:121], v[110:113], v[66:81]
	ds_read_b128 v[110:113], v164 offset:16384
	ds_read_b128 v[118:121], v164 offset:24576
	v_add_u32_e32 v164, s9, v179
	ds_read_b128 v[172:175], v164 offset:32768
	ds_read_b128 v[176:179], v164 offset:36864
	v_add_u32_e32 v164, s9, v180
	ds_read_b128 v[202:205], v164 offset:32768
	ds_read_b128 v[206:209], v164 offset:36864
	v_add_u32_e32 v164, s9, v181
	s_waitcnt lgkmcnt(9)
	v_mfma_f32_32x32x16_bf16 v[82:97], v[114:117], v[106:109], v[82:97]
	ds_read_b128 v[114:117], v163
	ds_read_b128 v[210:213], v163 offset:1024
	ds_read_b128 v[214:217], v164 offset:32768
	ds_read_b128 v[218:221], v164 offset:36864
	v_add_u32_e32 v164, s9, v182
	ds_read_b128 v[180:183], v164 offset:32768
	ds_read_b128 v[222:225], v164 offset:36864
	s_waitcnt lgkmcnt(14)
	v_mfma_f32_32x32x16_bf16 v[66:81], v[122:125], v[106:109], v[66:81]
	ds_read_b128 v[106:109], v163 offset:2048
	ds_read_b128 v[122:125], v163 offset:3072
	s_waitcnt lgkmcnt(14)
	v_mfma_f32_32x32x16_bf16 v[82:97], v[126:129], v[102:105], v[82:97]
	v_exp_f32_e32 v126, v133
	v_exp_f32_e32 v127, v148
	v_exp_f32_e32 v128, v149
	v_exp_f32_e32 v129, v150
	v_exp_f32_e32 v133, v151
	v_exp_f32_e32 v148, v154
	v_exp_f32_e32 v149, v155
	v_mfma_f32_32x32x16_bf16 v[66:81], v[140:143], v[102:105], v[66:81]
	v_add_f32_e32 v102, 0, v191
	v_add_f32_e32 v102, v192, v102
	v_add_f32_e32 v102, v194, v102
	v_add_f32_e32 v102, v196, v102
	v_add_f32_e32 v102, v198, v102
	v_add_f32_e32 v102, v200, v102
	v_add_f32_e32 v102, v197, v102
	s_waitcnt lgkmcnt(13)
	v_mfma_f32_32x32x16_bf16 v[82:97], v[110:113], v[98:101], v[82:97]
	v_add_f32_e32 v102, v199, v102
	v_add_f32_e32 v102, v185, v102
	v_add_f32_e32 v102, v186, v102
	v_exp_f32_e32 v140, v152
	v_exp_f32_e32 v141, v153
	v_exp_f32_e32 v142, v156
	v_exp_f32_e32 v143, v157
	s_waitcnt lgkmcnt(12)
	v_mfma_f32_32x32x16_bf16 v[66:81], v[118:121], v[98:101], v[66:81]
	v_add_f32_e32 v98, v188, v102
	v_add_f32_e32 v98, v190, v98
	v_add_f32_e32 v98, v187, v98
	v_add_f32_e32 v98, v189, v98
	v_add_f32_e32 v98, v193, v98
	v_add_f32_e32 v98, v195, v98
	v_add_f32_e32 v98, v130, v98
	s_waitcnt lgkmcnt(7)
	v_mfma_f32_32x32x16_bf16 v[82:97], v[172:175], v[114:117], v[82:97]
	v_add_f32_e32 v98, v131, v98
	v_add_f32_e32 v98, v146, v98
	v_add_f32_e32 v98, v147, v98
	v_add_f32_e32 v98, v132, v98
	v_add_f32_e32 v98, v126, v98
	v_add_f32_e32 v98, v127, v98
	v_add_f32_e32 v98, v128, v98
	v_mfma_f32_32x32x16_bf16 v[66:81], v[176:179], v[114:117], v[66:81]
	v_add_f32_e32 v98, v129, v98
	v_add_f32_e32 v98, v133, v98
	v_add_f32_e32 v98, v148, v98
	v_add_f32_e32 v98, v149, v98
	v_add_f32_e32 v98, v140, v98
	v_add_f32_e32 v98, v141, v98
	v_add_f32_e32 v98, v142, v98
	s_waitcnt lgkmcnt(6)
	v_mfma_f32_32x32x16_bf16 v[82:97], v[202:205], v[210:213], v[82:97]
	v_add_f32_e32 v99, v143, v98
	v_mov_b32_e32 v100, v99
	s_nop 1
	v_permlane32_swap_b32_e32 v99, v100
	v_cvt_pk_bf16_f32 v102, v191, v192
	v_cvt_pk_bf16_f32 v103, v194, v196
	v_cvt_pk_bf16_f32 v104, v198, v200
	v_mfma_f32_32x32x16_bf16 v[66:81], v[206:209], v[210:213], v[66:81]
	v_cvt_pk_bf16_f32 v105, v197, v199
	v_cvt_pk_bf16_f32 v110, v185, v186
	v_cvt_pk_bf16_f32 v111, v188, v190
	v_cvt_pk_bf16_f32 v112, v187, v189
	v_cvt_pk_bf16_f32 v113, v193, v195
	v_cvt_pk_bf16_f32 v114, v130, v131
	v_cvt_pk_bf16_f32 v115, v146, v147
	s_waitcnt lgkmcnt(1)
; #define RESC(a) do { if (__any((a) < 1.f)) { if (hi == 0) al_l[r32] = (a); asm volatile("s_waitcnt lgkmcnt(0)" ::: "memory"); \
;     _Pragma("unroll") for (int d = 0; d < 4; ++d) _Pragma("unroll") for (int r = 0; r < 16; ++r) o[d][r] *= al_l[crow(r, hi)]; } } while (0)
; DI void pv_sm(f32x16* o, int vb, bf16x8 pa0, bf16x8 pa1, bf16x8 pa2, bf16x8 pa3, f32x16& p0, f32x16& p1, float& m_reg, float& mn, float& alpha) {
;   PV_BLOCK(0)
;   float pm0 = p0[0];
; #pragma unroll
;   for (int r = 1; r < 16; ++r) pm0 = fmaxf(pm0, p0[r]);
;   PV_BLOCK(1)
;   float pmax = pm0;
; #pragma unroll
;   for (int r = 0; r < 16; ++r) pmax = fmaxf(pmax, p1[r]);
;   { auto rr = __builtin_amdgcn_permlane32_swap(__float_as_uint(pmax), __float_as_uint(pmax), false, false);
;     pmax = fmaxf(__uint_as_float(rr[0]), __uint_as_float(rr[1])); }
;   const bool keep = __all(pmax - m_reg <= ATH);
;   mn = keep ? m_reg : fmaxf(m_reg, pmax);
;   alpha = __builtin_amdgcn_exp2f(m_reg - mn);
;   m_reg = mn;
;   PV_BLOCK(2)
; #pragma unroll
;   for (int r = 0; r < 16; ++r) { p0[r] = p0[r] - mn; p1[r] = p1[r] - mn; }
;   PV_BLOCK(3)
; #pragma unroll
;   for (int r = 0; r < 16; ++r) p0[r] = __builtin_amdgcn_exp2f(p0[r]);
; }
; DI void attn_unit(const bf16_t* __restrict__ Qb, const bf16_t* __restrict__ Kh, const bf16_t* __restrict__ Vh, const bf16_t* __restrict__ Ph,
;                   bf16_t* __restrict__ Ob, int seq, float* __restrict__ lse_out, char* lds) {
;     ...
;   pv_sm(o, vb0 + sV, pa0, pa1, pa2, pa3, pB0, pB1, m_reg, mnB, alB);
;   __syncthreads(); RESC(alB);
	v_mfma_f32_32x32x16_bf16 v[82:97], v[214:217], v[106:109], v[82:97]
	v_cvt_pk_bf16_f32 v116, v132, v126
	v_cvt_pk_bf16_f32 v117, v127, v128
	v_permlane32_swap_b32_e32 v102, v104
	v_permlane32_swap_b32_e32 v103, v105
	v_permlane32_swap_b32_e32 v110, v112
	v_mfma_f32_32x32x16_bf16 v[66:81], v[218:221], v[106:109], v[66:81]
	v_cvt_pk_bf16_f32 v106, v129, v133
	v_cvt_pk_bf16_f32 v107, v148, v149
	v_cvt_pk_bf16_f32 v108, v140, v141
	v_cvt_pk_bf16_f32 v109, v142, v143
	v_permlane32_swap_b32_e32 v111, v113
	v_permlane32_swap_b32_e32 v114, v116
	s_waitcnt lgkmcnt(0)
	v_mfma_f32_32x32x16_bf16 v[82:97], v[180:183], v[122:125], v[82:97]
	v_permlane32_swap_b32_e32 v115, v117
	v_permlane32_swap_b32_e32 v106, v108
	v_permlane32_swap_b32_e32 v107, v109
	v_mfma_f32_32x32x16_bf16 v[66:81], v[222:225], v[122:125], v[66:81]
	v_add_u32_e32 v146, s6, v171
	ds_read_b64_tr_b16 v[118:119], v146 offset:0
	ds_read_b64_tr_b16 v[120:121], v146 offset:0x800
	ds_read_b64_tr_b16 v[122:123], v146 offset:0x1000
	ds_read_b64_tr_b16 v[124:125], v146 offset:0x1800
	ds_read_b64_tr_b16 v[126:127], v146 offset:0x2000
	ds_read_b64_tr_b16 v[128:129], v146 offset:0x2800
	ds_read_b64_tr_b16 v[130:131], v146 offset:0x3000
	ds_read_b64_tr_b16 v[132:133], v146 offset:0x3800
	s_waitcnt lgkmcnt(0)
	s_nop 0
	v_mfma_f32_32x32x16_bf16 v[2:17], v[102:105], v[118:121], v[2:17]
	ds_read_b64_tr_b16 v[118:119], v146 offset:0x200
	ds_read_b64_tr_b16 v[120:121], v146 offset:0xa00
	s_nop 4
	v_max_f32_e32 v98, v83, v83
	v_max_f32_e32 v101, v82, v82
	v_max_f32_e32 v98, v101, v98
	v_max3_f32 v98, v98, v84, v85
	v_max3_f32 v98, v98, v86, v87
	v_mfma_f32_32x32x16_bf16 v[2:17], v[110:113], v[122:125], v[2:17]
	ds_read_b64_tr_b16 v[122:123], v146 offset:0x1200
	ds_read_b64_tr_b16 v[124:125], v146 offset:0x1a00
	v_max3_f32 v98, v98, v88, v89
	v_max3_f32 v98, v98, v90, v91
	v_max3_f32 v98, v98, v92, v93
	v_max3_f32 v98, v98, v94, v95
	v_max3_f32 v98, v98, v96, v97
	v_mfma_f32_32x32x16_bf16 v[2:17], v[114:117], v[126:129], v[2:17]
	ds_read_b64_tr_b16 v[126:127], v146 offset:0x2200
	ds_read_b64_tr_b16 v[128:129], v146 offset:0x2a00
	ds_read_b64_tr_b16 v[140:141], v146 offset:0x3200
	ds_read_b64_tr_b16 v[142:143], v146 offset:0x3a00
	s_waitcnt lgkmcnt(0)
	v_mfma_f32_32x32x16_bf16 v[2:17], v[106:109], v[130:133], v[2:17]
	v_mfma_f32_32x32x16_bf16 v[50:65], v[102:105], v[118:121], v[50:65]
	v_max3_f32 v98, v98, v66, v67
	v_max3_f32 v98, v98, v68, v69
	v_max3_f32 v98, v98, v70, v71
	v_max3_f32 v98, v98, v72, v73
	v_max3_f32 v98, v98, v74, v75
	v_max3_f32 v98, v98, v76, v77
	v_max3_f32 v98, v98, v78, v79
	v_mfma_f32_32x32x16_bf16 v[50:65], v[110:113], v[122:125], v[50:65]
	v_max3_f32 v98, v98, v80, v81
	v_mov_b32_e32 v101, v98
	s_nop 1
	v_permlane32_swap_b32_e32 v98, v101
	v_max_f32_e32 v101, v101, v101
	v_max_f32_e32 v98, v98, v98
	v_max_f32_e32 v98, v98, v101
	v_mfma_f32_32x32x16_bf16 v[50:65], v[114:117], v[126:129], v[50:65]
	ds_read_b64_tr_b16 v[118:119], v146 offset:0x400
	v_sub_f32_e32 v101, v98, v144
	ds_read_b64_tr_b16 v[120:121], v146 offset:0xc00
	v_cmp_ge_f32_e32 vcc, s54, v101
	ds_read_b64_tr_b16 v[122:123], v146 offset:0x1400
	s_cmp_eq_u64 vcc, exec
	v_max_f32_e32 v101, v144, v144
	ds_read_b64_tr_b16 v[124:125], v146 offset:0x1c00
	v_mfma_f32_32x32x16_bf16 v[50:65], v[106:109], v[140:143], v[50:65]
	v_max_f32_e32 v98, v101, v98
	s_cselect_b64 vcc, -1, 0
	ds_read_b64_tr_b16 v[126:127], v146 offset:0x2400
	v_cndmask_b32_e32 v98, v98, v144, vcc
	ds_read_b64_tr_b16 v[128:129], v146 offset:0x2c00
	v_sub_f32_e32 v101, v144, v98
	ds_read_b64_tr_b16 v[130:131], v146 offset:0x3400
	v_exp_f32_e32 v101, v101
	ds_read_b64_tr_b16 v[132:133], v146 offset:0x3c00
	s_waitcnt lgkmcnt(0)
	v_mfma_f32_32x32x16_bf16 v[34:49], v[102:105], v[118:121], v[34:49]
	ds_read_b64_tr_b16 v[118:119], v146 offset:0x600
	ds_read_b64_tr_b16 v[120:121], v146 offset:0xe00
	v_mfma_f32_32x32x16_bf16 v[34:49], v[110:113], v[122:125], v[34:49]
	ds_read_b64_tr_b16 v[122:123], v146 offset:0x1600
	ds_read_b64_tr_b16 v[124:125], v146 offset:0x1e00
	v_mfma_f32_32x32x16_bf16 v[34:49], v[114:117], v[126:129], v[34:49]
	ds_read_b64_tr_b16 v[126:127], v146 offset:0x2600
	ds_read_b64_tr_b16 v[128:129], v146 offset:0x2e00
	ds_read_b64_tr_b16 v[140:141], v146 offset:0x3600
	ds_read_b64_tr_b16 v[142:143], v146 offset:0x3e00
	s_waitcnt lgkmcnt(0)
	v_mfma_f32_32x32x16_bf16 v[34:49], v[106:109], v[130:133], v[34:49]
	v_mfma_f32_32x32x16_bf16 v[18:33], v[102:105], v[118:121], v[18:33]
	v_cmp_gt_f32_e32 vcc, 1.0, v101
	s_barrier
	v_mfma_f32_32x32x16_bf16 v[18:33], v[110:113], v[122:125], v[18:33]
	v_mfma_f32_32x32x16_bf16 v[18:33], v[114:117], v[126:129], v[18:33]
	v_mfma_f32_32x32x16_bf16 v[18:33], v[106:109], v[140:143], v[18:33]
	s_cbranch_vccz .LBB0_679
	s_and_saveexec_b64 s[4:5], s[2:3]
	ds_write_b32 v161, v101 offset:128
	s_or_b64 exec, exec, s[4:5]
	s_waitcnt lgkmcnt(0)
	v_add_u32_e32 v114, v137, v134
	ds_read_b128 v[102:105], v114 offset:224
	ds_read_b128 v[106:109], v114 offset:192
	ds_read_b128 v[110:113], v114 offset:160
	ds_read_b128 v[114:117], v114 offset:128
	s_waitcnt lgkmcnt(3)
	v_pk_mul_f32 v[14:15], v[14:15], v[102:103]
	s_waitcnt lgkmcnt(2)
	v_pk_mul_f32 v[10:11], v[10:11], v[106:107]
	s_waitcnt lgkmcnt(1)
	v_pk_mul_f32 v[6:7], v[6:7], v[110:111]
	v_pk_mul_f32 v[16:17], v[16:17], v[104:105]
	v_pk_mul_f32 v[12:13], v[12:13], v[108:109]
	v_pk_mul_f32 v[8:9], v[8:9], v[112:113]
	s_waitcnt lgkmcnt(0)
	v_pk_mul_f32 v[4:5], v[4:5], v[116:117]
	v_pk_mul_f32 v[2:3], v[2:3], v[114:115]
	v_pk_mul_f32 v[62:63], v[62:63], v[102:103]
	v_pk_mul_f32 v[58:59], v[58:59], v[106:107]
	v_pk_mul_f32 v[54:55], v[54:55], v[110:111]
	v_pk_mul_f32 v[64:65], v[64:65], v[104:105]
	v_pk_mul_f32 v[60:61], v[60:61], v[108:109]
	v_pk_mul_f32 v[56:57], v[56:57], v[112:113]
	v_pk_mul_f32 v[52:53], v[52:53], v[116:117]
	v_pk_mul_f32 v[50:51], v[50:51], v[114:115]
	v_pk_mul_f32 v[46:47], v[46:47], v[102:103]
	v_pk_mul_f32 v[42:43], v[42:43], v[106:107]
	v_pk_mul_f32 v[38:39], v[38:39], v[110:111]
	v_pk_mul_f32 v[48:49], v[48:49], v[104:105]
	v_pk_mul_f32 v[44:45], v[44:45], v[108:109]
	v_pk_mul_f32 v[40:41], v[40:41], v[112:113]
	v_pk_mul_f32 v[36:37], v[36:37], v[116:117]
	v_pk_mul_f32 v[34:35], v[34:35], v[114:115]
	v_pk_mul_f32 v[30:31], v[30:31], v[102:103]
	v_pk_mul_f32 v[26:27], v[26:27], v[106:107]
	v_pk_mul_f32 v[22:23], v[22:23], v[110:111]
	v_pk_mul_f32 v[32:33], v[32:33], v[104:105]
	v_pk_mul_f32 v[28:29], v[28:29], v[108:109]
	v_pk_mul_f32 v[24:25], v[24:25], v[112:113]
	v_pk_mul_f32 v[20:21], v[20:21], v[116:117]
	v_pk_mul_f32 v[18:19], v[18:19], v[114:115]
